# v26 plus gMLP W_s fragment loads hoisted (18 up front, counted waits) plus residual/gate loads of P4a P4b P5 P9 epilogues hoisted into dead fragment VGPRs
# baseline (speedup 1.0000x reference)
; #define LAS __attribute__((address_space(3)))
; __device__ __forceinline__ void gmlp_item(Frame& F, int item, bool dry = false) {
;     ...
;     __syncthreads();
;     const int li = lane & 15, lq = lane >> 4;
;     f32x4 acc[2][8];
; #pragma unroll
;     for (int db = 0; db < 2; ++db)
; #pragma unroll
;         for (int ib = 0; ib < 8; ++ib) acc[db][ib] = (f32x4){0.f, 0.f, 0.f, 0.f};
;     bf16x8 af[2][4];
; #pragma unroll
;     for (int db = 0; db < 2; ++db)
; #pragma unroll
;         for (int ks = 0; ks < 4; ++ks) af[db][ks] = *(const LAS bf16x8*)(VT + (32 * F.wave + 16 * db + li) * VT_PITCH + (32 * ks + 8 * lq) * 2);
;     const bf16* Wg = WSP(bf16, WS_WSB) + (size_t)g * 128 * 128;
; #pragma unroll
;     for (int ib = 0; ib < 8; ++ib) {
;         if (samp && ib >= 2) continue;
; #pragma unroll
;         for (int ks = 0; ks < 4; ++ks) {
;             if (ks >= (ib < 4 ? 2 : 4)) continue;
;             if (samp && ks >= 1) continue;
;             const bf16x8 bfr = *(const bf16x8*)(Wg + (16 * ib + li) * 128 + 32 * ks + 8 * lq);
; #pragma unroll
;             for (int db = 0; db < 2; ++db) acc[db][ib] = __builtin_amdgcn_mfma_f32_16x16x32_bf16(af[db][ks], bfr, acc[db][ib], 0, 0, 0);
;         }
;     }
.LBB0_855:
	v_and_b32_e32 v107, 15, v44
	s_lshl_b32 s6, s56, 15
	v_bfe_u32 v106, v44, 4, 2
	v_or_b32_e32 v2, s25, v107
	s_add_u32 s6, s2, s6
	v_lshlrev_b32_e32 v100, 4, v106
	v_mul_lo_u32 v2, v2, s31
	s_addc_u32 s7, s26, 0
	v_add3_u32 v6, 0, v100, v2
	v_lshl_add_u64 v[2:3], s[6:7], 0, v[100:101]
	v_lshlrev_b32_e32 v100, 8, v107
	v_lshl_add_u64 v[102:103], v[2:3], 0, v[100:101]
	s_waitcnt lgkmcnt(0)
	s_barrier
	v_lshlrev_b32_e32 v239, 8, v107
	v_lshl_or_b32 v239, v106, 4, v239
	s_mov_b64 s[98:99], s[6:7]
	global_load_dwordx4 v[112:115], v239, s[98:99]
	global_load_dwordx4 v[116:119], v239, s[98:99] offset:64
	s_add_u32 s98, s6, 0x1000
	s_addc_u32 s99, s7, 0
	global_load_dwordx4 v[120:123], v239, s[98:99]
	global_load_dwordx4 v[124:127], v239, s[98:99] offset:64
	s_add_u32 s98, s6, 0x2000
	s_addc_u32 s99, s7, 0
	global_load_dwordx4 v[128:131], v239, s[98:99]
	global_load_dwordx4 v[132:135], v239, s[98:99] offset:64
	s_add_u32 s98, s6, 0x3000
	s_addc_u32 s99, s7, 0
	global_load_dwordx4 v[136:139], v239, s[98:99]
	global_load_dwordx4 v[140:143], v239, s[98:99] offset:64
	s_add_u32 s98, s6, 0x4000
	s_addc_u32 s99, s7, 0
	global_load_dwordx4 v[144:147], v239, s[98:99]
	global_load_dwordx4 v[148:151], v239, s[98:99] offset:64
	global_load_dwordx4 v[152:155], v239, s[98:99] offset:128
	global_load_dwordx4 v[156:159], v239, s[98:99] offset:192
	s_add_u32 s98, s6, 0x5000
	s_addc_u32 s99, s7, 0
	global_load_dwordx4 v[160:163], v239, s[98:99]
	global_load_dwordx4 v[182:185], v239, s[98:99] offset:64
	global_load_dwordx4 v[186:189], v239, s[98:99] offset:128
	global_load_dwordx4 v[230:233], v239, s[98:99] offset:192
	s_add_u32 s98, s6, 0x6000
	s_addc_u32 s99, s7, 0
	global_load_dwordx4 v[240:243], v239, s[98:99]
	global_load_dwordx4 v[244:247], v239, s[98:99] offset:64
	ds_read_b128 v[78:81], v6
	ds_read_b128 v[82:85], v6 offset:4352
	ds_read_b128 v[90:93], v6 offset:64
	ds_read_b128 v[70:73], v6 offset:128
	ds_read_b128 v[66:69], v6 offset:192
	ds_read_b128 v[94:97], v6 offset:4416
	ds_read_b128 v[86:89], v6 offset:4480
	ds_read_b128 v[74:77], v6 offset:4544
	s_and_b64 vcc, exec, s[4:5]
	s_waitcnt vmcnt(17) lgkmcnt(7)
	v_mfma_f32_16x16x32_bf16 v[62:65], v[78:81], v[112:115], 0
	s_waitcnt lgkmcnt(6)
	v_mfma_f32_16x16x32_bf16 v[58:61], v[82:85], v[112:115], 0
	s_cbranch_vccnz .LBB0_857
	s_waitcnt vmcnt(16) lgkmcnt(5)
	v_mfma_f32_16x16x32_bf16 v[62:65], v[90:93], v[116:119], v[62:65]
	s_waitcnt lgkmcnt(2)
	v_mfma_f32_16x16x32_bf16 v[58:61], v[94:97], v[116:119], v[58:61]
.LBB0_857:
	s_and_b64 vcc, exec, s[4:5]
	s_waitcnt vmcnt(15)
	v_mfma_f32_16x16x32_bf16 v[54:57], v[78:81], v[120:123], 0
	v_mfma_f32_16x16x32_bf16 v[50:53], v[82:85], v[120:123], 0
	s_cbranch_vccnz .LBB0_859
	s_waitcnt vmcnt(14) lgkmcnt(5)
	v_mfma_f32_16x16x32_bf16 v[54:57], v[90:93], v[124:127], v[54:57]
	s_waitcnt lgkmcnt(2)
	v_mfma_f32_16x16x32_bf16 v[50:53], v[94:97], v[124:127], v[50:53]
.LBB0_859:
	s_add_u32 s98, s6, 0x6000
	s_addc_u32 s99, s7, 0
	global_load_dwordx4 v[112:115], v239, s[98:99] offset:128
	global_load_dwordx4 v[116:119], v239, s[98:99] offset:192
	s_add_u32 s98, s6, 0x7000
	s_addc_u32 s99, s7, 0
	global_load_dwordx4 v[120:123], v239, s[98:99]
	global_load_dwordx4 v[124:127], v239, s[98:99] offset:64
	v_mov_b32_e32 v10, 0
	s_and_b64 vcc, exec, s[4:5]
	v_mov_b32_e32 v30, 0
	v_mov_b32_e32 v31, 0
	v_mov_b32_e32 v32, 0
	v_mov_b32_e32 v33, 0
	v_mov_b32_e32 v46, 0
	v_mov_b32_e32 v47, 0
	v_mov_b32_e32 v48, 0
	v_mov_b32_e32 v49, 0
	s_cbranch_vccnz .LBB0_861
	s_nop 0
	s_waitcnt vmcnt(17)
	v_mfma_f32_16x16x32_bf16 v[12:15], v[78:81], v[128:131], 0
	v_mfma_f32_16x16x32_bf16 v[2:5], v[82:85], v[128:131], 0
	s_waitcnt vmcnt(16) lgkmcnt(5)
	v_mfma_f32_16x16x32_bf16 v[46:49], v[90:93], v[132:135], v[12:15]
	s_waitcnt lgkmcnt(2)
	v_mfma_f32_16x16x32_bf16 v[30:33], v[94:97], v[132:135], v[2:5]
; __device__ __forceinline__ void gmlp_item(Frame& F, int item, bool dry = false) {
;     ...
;     const bf16* Wg = WSP(bf16, WS_WSB) + (size_t)g * 128 * 128;
; #pragma unroll
;     for (int ib = 0; ib < 8; ++ib) {
;         if (samp && ib >= 2) continue;
; #pragma unroll
;         for (int ks = 0; ks < 4; ++ks) {
;             if (ks >= (ib < 4 ? 2 : 4)) continue;
;             if (samp && ks >= 1) continue;
;             const bf16x8 bfr = *(const bf16x8*)(Wg + (16 * ib + li) * 128 + 32 * ks + 8 * lq);
; #pragma unroll
;             for (int db = 0; db < 2; ++db) acc[db][ib] = __builtin_amdgcn_mfma_f32_16x16x32_bf16(af[db][ks], bfr, acc[db][ib], 0, 0, 0);
;         }
;     }
.LBB0_861:
	s_add_u32 s98, s6, 0x7000
	s_addc_u32 s99, s7, 0
	global_load_dwordx4 v[128:131], v239, s[98:99] offset:128
	global_load_dwordx4 v[132:135], v239, s[98:99] offset:192
	s_and_b64 vcc, exec, s[4:5]
	v_mov_b32_e32 v11, 0
	s_nop 0
	v_mov_b32_e32 v12, 0
	v_mov_b32_e32 v13, 0
	v_mov_b32_e32 v42, 0
	v_mov_b32_e32 v43, 0
	v_mov_b32_e32 v44, 0
	v_mov_b32_e32 v45, 0
	s_cbranch_vccnz .LBB0_863
	s_nop 0
	s_waitcnt vmcnt(17)
	v_mfma_f32_16x16x32_bf16 v[10:13], v[78:81], v[136:139], 0
	v_mfma_f32_16x16x32_bf16 v[2:5], v[82:85], v[136:139], 0
	s_waitcnt vmcnt(16) lgkmcnt(5)
	v_mfma_f32_16x16x32_bf16 v[42:45], v[90:93], v[140:143], v[10:13]
	s_waitcnt lgkmcnt(2)
	v_mfma_f32_16x16x32_bf16 v[10:13], v[94:97], v[140:143], v[2:5]
.LBB0_863:
	v_mov_b32_e32 v6, 0
	s_and_b64 vcc, exec, s[4:5]
	v_mov_b32_e32 v18, 0
	v_mov_b32_e32 v19, 0
	v_mov_b32_e32 v20, 0
	v_mov_b32_e32 v21, 0
	v_mov_b32_e32 v38, 0
	v_mov_b32_e32 v39, 0
	v_mov_b32_e32 v40, 0
	v_mov_b32_e32 v41, 0
	s_cbranch_vccnz .LBB0_865
	s_waitcnt vmcnt(15)
	v_mfma_f32_16x16x32_bf16 v[18:21], v[78:81], v[144:147], 0
	v_mfma_f32_16x16x32_bf16 v[2:5], v[82:85], v[144:147], 0
	s_waitcnt vmcnt(14) lgkmcnt(5)
	v_mfma_f32_16x16x32_bf16 v[18:21], v[90:93], v[148:151], v[18:21]
	s_waitcnt lgkmcnt(2)
	v_mfma_f32_16x16x32_bf16 v[2:5], v[94:97], v[148:151], v[2:5]
	s_waitcnt vmcnt(13)
	v_mfma_f32_16x16x32_bf16 v[18:21], v[70:73], v[152:155], v[18:21]
	s_waitcnt lgkmcnt(1)
	v_mfma_f32_16x16x32_bf16 v[2:5], v[86:89], v[152:155], v[2:5]
	s_waitcnt vmcnt(12)
	v_mfma_f32_16x16x32_bf16 v[38:41], v[66:69], v[156:159], v[18:21]
	s_waitcnt lgkmcnt(0)
	v_mfma_f32_16x16x32_bf16 v[18:21], v[74:77], v[156:159], v[2:5]
.LBB0_865:
	s_and_b64 vcc, exec, s[4:5]
	v_mov_b32_e32 v7, 0
	v_mov_b32_e32 v8, 0
	v_mov_b32_e32 v9, 0
	v_mov_b32_e32 v34, 0
	v_mov_b32_e32 v35, 0
	v_mov_b32_e32 v36, 0
	v_mov_b32_e32 v37, 0
	s_cbranch_vccnz .LBB0_867
	s_waitcnt vmcnt(11)
	v_mfma_f32_16x16x32_bf16 v[14:17], v[78:81], v[160:163], 0
	v_mfma_f32_16x16x32_bf16 v[2:5], v[82:85], v[160:163], 0
	s_waitcnt vmcnt(10) lgkmcnt(5)
	v_mfma_f32_16x16x32_bf16 v[14:17], v[90:93], v[182:185], v[14:17]
	s_waitcnt lgkmcnt(2)
	v_mfma_f32_16x16x32_bf16 v[2:5], v[94:97], v[182:185], v[2:5]
	s_waitcnt vmcnt(9)
	v_mfma_f32_16x16x32_bf16 v[14:17], v[70:73], v[186:189], v[14:17]
	s_waitcnt lgkmcnt(1)
	v_mfma_f32_16x16x32_bf16 v[2:5], v[86:89], v[186:189], v[2:5]
	s_waitcnt vmcnt(8)
	v_mfma_f32_16x16x32_bf16 v[34:37], v[66:69], v[230:233], v[14:17]
	s_waitcnt lgkmcnt(0)
	v_mfma_f32_16x16x32_bf16 v[6:9], v[74:77], v[230:233], v[2:5]
.LBB0_867:
	s_nop 3
	v_mov_b32_e32 v2, 0
	s_and_b64 vcc, exec, s[4:5]
	v_mov_b32_e32 v14, 0
	v_mov_b32_e32 v15, 0
	v_mov_b32_e32 v16, 0
	v_mov_b32_e32 v17, 0
	v_mov_b32_e32 v26, 0
	v_mov_b32_e32 v27, 0
	v_mov_b32_e32 v28, 0
	v_mov_b32_e32 v29, 0
	s_cbranch_vccnz .LBB0_869
	s_waitcnt vmcnt(7)
	v_mfma_f32_16x16x32_bf16 v[26:29], v[78:81], v[240:243], 0
	v_mfma_f32_16x16x32_bf16 v[14:17], v[82:85], v[240:243], 0
	s_waitcnt vmcnt(6) lgkmcnt(5)
	v_mfma_f32_16x16x32_bf16 v[26:29], v[90:93], v[244:247], v[26:29]
	s_waitcnt lgkmcnt(2)
	v_mfma_f32_16x16x32_bf16 v[14:17], v[94:97], v[244:247], v[14:17]
	s_waitcnt vmcnt(5)
	v_mfma_f32_16x16x32_bf16 v[26:29], v[70:73], v[112:115], v[26:29]
	s_waitcnt lgkmcnt(1)
	v_mfma_f32_16x16x32_bf16 v[14:17], v[86:89], v[112:115], v[14:17]
	s_waitcnt vmcnt(4)
	v_mfma_f32_16x16x32_bf16 v[26:29], v[66:69], v[116:119], v[26:29]
	s_waitcnt lgkmcnt(0)
	v_mfma_f32_16x16x32_bf16 v[14:17], v[74:77], v[116:119], v[14:17]
.LBB0_869:
	s_and_b64 vcc, exec, s[4:5]
	v_mov_b32_e32 v3, 0
	v_mov_b32_e32 v4, 0
	v_mov_b32_e32 v5, 0
	v_mov_b32_e32 v22, 0
	v_mov_b32_e32 v23, 0
	v_mov_b32_e32 v24, 0
	v_mov_b32_e32 v25, 0
	s_cbranch_vccnz .LBB0_871
	s_waitcnt vmcnt(3)
	v_mfma_f32_16x16x32_bf16 v[78:81], v[78:81], v[120:123], 0
	v_mfma_f32_16x16x32_bf16 v[2:5], v[82:85], v[120:123], 0
	s_waitcnt vmcnt(2) lgkmcnt(5)
	v_mfma_f32_16x16x32_bf16 v[78:81], v[90:93], v[124:127], v[78:81]
	s_waitcnt lgkmcnt(2)
	v_mfma_f32_16x16x32_bf16 v[2:5], v[94:97], v[124:127], v[2:5]
	s_waitcnt vmcnt(1)
	v_mfma_f32_16x16x32_bf16 v[22:25], v[70:73], v[128:131], v[78:81]
	s_waitcnt lgkmcnt(1)
	v_mfma_f32_16x16x32_bf16 v[2:5], v[86:89], v[128:131], v[2:5]
	s_waitcnt vmcnt(0)
	v_mfma_f32_16x16x32_bf16 v[22:25], v[66:69], v[132:135], v[22:25]
	s_waitcnt lgkmcnt(0)
	v_mfma_f32_16x16x32_bf16 v[2:5], v[74:77], v[132:135], v[2:5]

; __device__ __forceinline__ float bf_lo(unsigned w) { return __uint_as_float(w << 16); }
; __device__ __forceinline__ float bf_hi(unsigned w) { return __uint_as_float(w & 0xffff0000u); }
; __device__ __forceinline__ v4u pack8(f32x4 a, f32x4 b) { v4u w; w.x = cvt_pk_bf16(a[0], a[1]); w.y = cvt_pk_bf16(a[2], a[3]); w.z = cvt_pk_bf16(b[0], b[1]); w.w = cvt_pk_bf16(b[2], b[3]); return w; }
;     __device__ __forceinline__ void operator()(const f32x4 (&acc)[2][2][4][2], const Unit& u, int wr, int wc, int fr, int fq) const {
;     ...
;             for (int m = 0; m < 4; ++m) { const size_t off = (size_t)(row0 + ai * 128 + m * 16) * DM + col0;
; #pragma unroll
;                 for (int bj = 0; bj < 2; ++bj) { const v4u g = *(const v4u*)(SA + off + bj * 128); const f32x4 a0 = acc[ai][bj][m][0], a1 = acc[ai][bj][m][1];
;                     const f32x4 y0 = {a0[0] * bf_lo(g.x), a0[1] * bf_hi(g.x), a0[2] * bf_lo(g.y), a0[3] * bf_hi(g.y)};
;                     const f32x4 y1 = {a1[0] * bf_lo(g.z), a1[1] * bf_hi(g.z), a1[2] * bf_lo(g.w), a1[3] * bf_hi(g.w)};
;                     *(v4u*)(P + off + bj * 128) = pack8(y0, y1); } }
.LBB0_1065:
	v_lshl_add_u32 v150, s68, 8, v152
	v_lshl_or_b32 v148, s41, 8, v154
	v_ashrrev_i32_e32 v151, 31, v150
	v_ashrrev_i32_e32 v149, 31, v148
	v_lshlrev_b64 v[146:147], 12, v[150:151]
	v_lshl_add_u64 v[146:147], v[146:147], 0, v[148:149]
	v_lshlrev_b64 v[146:147], 1, v[146:147]
	v_lshl_add_u64 v[162:163], s[50:51], 0, v[146:147]
	global_load_dwordx4 v[158:161], v[162:163], off
	global_load_dwordx4 v[172:175], v[162:163], off offset:256
	v_or_b32_e32 v232, 16, v150
	v_ashrrev_i32_e32 v233, 31, v232
	v_lshlrev_b64 v[232:233], 12, v[232:233]
	v_lshl_add_u64 v[232:233], v[232:233], 0, v[148:149]
	v_lshlrev_b64 v[232:233], 1, v[232:233]
	v_lshl_add_u64 v[244:245], s[50:51], 0, v[232:233]
	global_load_dwordx4 v[176:179], v[244:245], off
	v_or_b32_e32 v232, 16, v150
	v_ashrrev_i32_e32 v233, 31, v232
	v_lshlrev_b64 v[232:233], 12, v[232:233]
	v_lshl_add_u64 v[232:233], v[232:233], 0, v[148:149]
	v_lshlrev_b64 v[232:233], 1, v[232:233]
	v_lshl_add_u64 v[244:245], s[50:51], 0, v[232:233]
	global_load_dwordx4 v[180:183], v[244:245], off offset:256
	v_or_b32_e32 v232, 32, v150
	v_ashrrev_i32_e32 v233, 31, v232
	v_lshlrev_b64 v[232:233], 12, v[232:233]
	v_lshl_add_u64 v[232:233], v[232:233], 0, v[148:149]
	v_lshlrev_b64 v[232:233], 1, v[232:233]
	v_lshl_add_u64 v[244:245], s[50:51], 0, v[232:233]
	global_load_dwordx4 v[184:187], v[244:245], off
	v_or_b32_e32 v232, 32, v150
	v_ashrrev_i32_e32 v233, 31, v232
	v_lshlrev_b64 v[232:233], 12, v[232:233]
	v_lshl_add_u64 v[232:233], v[232:233], 0, v[148:149]
	v_lshlrev_b64 v[232:233], 1, v[232:233]
	v_lshl_add_u64 v[244:245], s[50:51], 0, v[232:233]
	global_load_dwordx4 v[188:191], v[244:245], off offset:256
	v_or_b32_e32 v232, 48, v150
	v_ashrrev_i32_e32 v233, 31, v232
	v_lshlrev_b64 v[232:233], 12, v[232:233]
	v_lshl_add_u64 v[232:233], v[232:233], 0, v[148:149]
	v_lshlrev_b64 v[232:233], 1, v[232:233]
	v_lshl_add_u64 v[244:245], s[50:51], 0, v[232:233]
	global_load_dwordx4 v[192:195], v[244:245], off
	v_or_b32_e32 v232, 48, v150
	v_ashrrev_i32_e32 v233, 31, v232
	v_lshlrev_b64 v[232:233], 12, v[232:233]
	v_lshl_add_u64 v[232:233], v[232:233], 0, v[148:149]
	v_lshlrev_b64 v[232:233], 1, v[232:233]
	v_lshl_add_u64 v[244:245], s[50:51], 0, v[232:233]
	global_load_dwordx4 v[200:203], v[244:245], off offset:256
	v_lshl_add_u64 v[232:233], v[146:147], 0, s[52:53]
	v_lshl_add_u64 v[244:245], s[50:51], 0, v[232:233]
	global_load_dwordx4 v[204:207], v[244:245], off
	v_lshl_add_u64 v[232:233], v[146:147], 0, s[52:53]
	v_lshl_add_u64 v[244:245], s[50:51], 0, v[232:233]
	global_load_dwordx4 v[208:211], v[244:245], off offset:256
	v_lshl_add_u64 v[232:233], v[146:147], 0, s[54:55]
	v_lshl_add_u64 v[244:245], s[50:51], 0, v[232:233]
	global_load_dwordx4 v[212:215], v[244:245], off
	v_lshl_add_u64 v[232:233], v[146:147], 0, s[54:55]
	v_lshl_add_u64 v[244:245], s[50:51], 0, v[232:233]
	global_load_dwordx4 v[216:219], v[244:245], off offset:256
	v_lshl_add_u64 v[232:233], v[146:147], 0, s[56:57]
	v_lshl_add_u64 v[244:245], s[50:51], 0, v[232:233]
	global_load_dwordx4 v[220:223], v[244:245], off
	v_lshl_add_u64 v[232:233], v[146:147], 0, s[56:57]
	v_lshl_add_u64 v[244:245], s[50:51], 0, v[232:233]
	global_load_dwordx4 v[224:227], v[244:245], off offset:256
	v_lshl_add_u64 v[232:233], v[146:147], 0, s[58:59]
	v_lshl_add_u64 v[244:245], s[50:51], 0, v[232:233]
	global_load_dwordx4 v[228:231], v[244:245], off
	v_lshl_add_u64 v[232:233], v[146:147], 0, s[58:59]
	v_lshl_add_u64 v[244:245], s[50:51], 0, v[232:233]
	global_load_dwordx4 v[240:243], v[244:245], off offset:256
	v_lshl_add_u64 v[168:169], s[20:21], 0, v[146:147]
	s_andn2_b64 vcc, exec, s[4:5]
	s_mov_b64 s[4:5], -1
	s_waitcnt vmcnt(15)
	v_lshlrev_b32_e32 v171, 16, v161
	v_and_b32_e32 v161, 0xffff0000, v161
	v_lshlrev_b32_e32 v151, 16, v158
	v_and_b32_e32 v158, 0xffff0000, v158
	v_lshlrev_b32_e32 v166, 16, v159
	v_and_b32_e32 v159, 0xffff0000, v159
	v_lshlrev_b32_e32 v170, 16, v160
	v_and_b32_e32 v160, 0xffff0000, v160
	v_mul_f32_e32 v125, v125, v161
	v_mul_f32_e32 v126, v126, v151
	v_mul_f32_e32 v127, v127, v158
	v_mul_f32_e32 v128, v128, v166
	v_mul_f32_e32 v129, v129, v159
	v_mul_f32_e32 v151, v122, v170
	v_mul_f32_e32 v158, v123, v160
	v_mul_f32_e32 v159, v124, v171
	v_cvt_pk_bf16_f32 v122, v126, v127
	v_cvt_pk_bf16_f32 v123, v128, v129
	v_cvt_pk_bf16_f32 v124, v151, v158
	v_cvt_pk_bf16_f32 v125, v159, v125
	global_store_dwordx4 v[168:169], v[122:125], off
	v_or_b32_e32 v126, 16, v150
	v_ashrrev_i32_e32 v127, 31, v126
	v_lshlrev_b64 v[126:127], 12, v[126:127]
	v_lshl_add_u64 v[126:127], v[126:127], 0, v[148:149]
	v_lshlrev_b64 v[126:127], 1, v[126:127]
	v_lshl_add_u64 v[128:129], s[50:51], 0, v[126:127]
	s_waitcnt vmcnt(15)
	v_lshlrev_b32_e32 v160, 16, v175
	v_and_b32_e32 v125, 0xffff0000, v175
	v_lshlrev_b32_e32 v151, 16, v172
	v_and_b32_e32 v122, 0xffff0000, v172
	v_lshlrev_b32_e32 v158, 16, v173
	v_and_b32_e32 v123, 0xffff0000, v173
	v_lshlrev_b32_e32 v159, 16, v174
	v_and_b32_e32 v124, 0xffff0000, v174
	v_mul_f32_e32 v117, v117, v125
	v_mul_f32_e32 v118, v118, v151
	v_mul_f32_e32 v119, v119, v122
	v_mul_f32_e32 v120, v120, v158
	v_mul_f32_e32 v121, v121, v123
	v_mul_f32_e32 v122, v114, v159
	v_mul_f32_e32 v123, v115, v124
	v_mul_f32_e32 v124, v116, v160
	v_cvt_pk_bf16_f32 v114, v118, v119
	v_cvt_pk_bf16_f32 v115, v120, v121
	v_cvt_pk_bf16_f32 v116, v122, v123
	v_cvt_pk_bf16_f32 v117, v124, v117
	global_store_dwordx4 v[168:169], v[114:117], off offset:256
	v_lshl_add_u64 v[118:119], s[20:21], 0, v[126:127]
	s_waitcnt vmcnt(15)
; __device__ __forceinline__ float bf_lo(unsigned w) { return __uint_as_float(w << 16); }
; __device__ __forceinline__ float bf_hi(unsigned w) { return __uint_as_float(w & 0xffff0000u); }
; __device__ __forceinline__ v4u pack8(f32x4 a, f32x4 b) { v4u w; w.x = cvt_pk_bf16(a[0], a[1]); w.y = cvt_pk_bf16(a[2], a[3]); w.z = cvt_pk_bf16(b[0], b[1]); w.w = cvt_pk_bf16(b[2], b[3]); return w; }
;     __device__ __forceinline__ void operator()(const f32x4 (&acc)[2][2][4][2], const Unit& u, int wr, int wc, int fr, int fq) const {
;     ...
;             for (int m = 0; m < 4; ++m) { const size_t off = (size_t)(row0 + ai * 128 + m * 16) * DM + col0;
; #pragma unroll
;                 for (int bj = 0; bj < 2; ++bj) { const v4u g = *(const v4u*)(SA + off + bj * 128); const f32x4 a0 = acc[ai][bj][m][0], a1 = acc[ai][bj][m][1];
;                     const f32x4 y0 = {a0[0] * bf_lo(g.x), a0[1] * bf_hi(g.x), a0[2] * bf_lo(g.y), a0[3] * bf_hi(g.y)};
;                     const f32x4 y1 = {a1[0] * bf_lo(g.z), a1[1] * bf_hi(g.z), a1[2] * bf_lo(g.w), a1[3] * bf_hi(g.w)};
;                     *(v4u*)(P + off + bj * 128) = pack8(y0, y1); } }
	v_lshlrev_b32_e32 v123, 16, v179
	v_and_b32_e32 v117, 0xffff0000, v179
	v_lshlrev_b32_e32 v120, 16, v176
	v_and_b32_e32 v114, 0xffff0000, v176
	v_lshlrev_b32_e32 v121, 16, v177
	v_and_b32_e32 v115, 0xffff0000, v177
	v_lshlrev_b32_e32 v122, 16, v178
	v_and_b32_e32 v116, 0xffff0000, v178
	v_mul_f32_e32 v109, v109, v117
	v_mul_f32_e32 v110, v110, v120
	v_mul_f32_e32 v111, v111, v114
	v_mul_f32_e32 v112, v112, v121
	v_mul_f32_e32 v113, v113, v115
	v_mul_f32_e32 v114, v106, v122
	v_mul_f32_e32 v115, v107, v116
	v_mul_f32_e32 v116, v108, v123
	v_cvt_pk_bf16_f32 v106, v110, v111
	v_cvt_pk_bf16_f32 v107, v112, v113
	v_cvt_pk_bf16_f32 v108, v114, v115
	v_cvt_pk_bf16_f32 v109, v116, v109
	global_store_dwordx4 v[118:119], v[106:109], off
	v_or_b32_e32 v110, 32, v150
	v_ashrrev_i32_e32 v111, 31, v110
	v_lshlrev_b64 v[110:111], 12, v[110:111]
	v_lshl_add_u64 v[110:111], v[110:111], 0, v[148:149]
	v_lshlrev_b64 v[110:111], 1, v[110:111]
	v_lshl_add_u64 v[112:113], s[50:51], 0, v[110:111]
	s_waitcnt vmcnt(15)
	v_lshlrev_b32_e32 v117, 16, v183
	v_and_b32_e32 v109, 0xffff0000, v183
	v_lshlrev_b32_e32 v114, 16, v180
	v_and_b32_e32 v106, 0xffff0000, v180
	v_lshlrev_b32_e32 v115, 16, v181
	v_and_b32_e32 v107, 0xffff0000, v181
	v_lshlrev_b32_e32 v116, 16, v182
	v_and_b32_e32 v108, 0xffff0000, v182
	v_mul_f32_e32 v101, v101, v109
	v_mul_f32_e32 v102, v102, v114
	v_mul_f32_e32 v103, v103, v106
	v_mul_f32_e32 v104, v104, v115
	v_mul_f32_e32 v105, v105, v107
	v_mul_f32_e32 v106, v98, v116
	v_mul_f32_e32 v107, v99, v108
	v_mul_f32_e32 v108, v100, v117
	v_cvt_pk_bf16_f32 v98, v102, v103
	v_cvt_pk_bf16_f32 v99, v104, v105
	v_cvt_pk_bf16_f32 v100, v106, v107
	v_cvt_pk_bf16_f32 v101, v108, v101
	global_store_dwordx4 v[118:119], v[98:101], off offset:256
	v_lshl_add_u64 v[102:103], s[20:21], 0, v[110:111]
	s_waitcnt vmcnt(15)
	v_lshlrev_b32_e32 v107, 16, v187
	v_and_b32_e32 v101, 0xffff0000, v187
	v_lshlrev_b32_e32 v104, 16, v184
	v_and_b32_e32 v98, 0xffff0000, v184
	v_lshlrev_b32_e32 v105, 16, v185
	v_and_b32_e32 v99, 0xffff0000, v185
	v_lshlrev_b32_e32 v106, 16, v186
	v_and_b32_e32 v100, 0xffff0000, v186
	v_mul_f32_e32 v93, v93, v101
	v_mul_f32_e32 v94, v94, v104
	v_mul_f32_e32 v95, v95, v98
	v_mul_f32_e32 v96, v96, v105
	v_mul_f32_e32 v97, v97, v99
	v_mul_f32_e32 v98, v90, v106
	v_mul_f32_e32 v99, v91, v100
	v_mul_f32_e32 v100, v92, v107
	v_cvt_pk_bf16_f32 v90, v94, v95
	v_cvt_pk_bf16_f32 v91, v96, v97
	v_cvt_pk_bf16_f32 v92, v98, v99
	v_cvt_pk_bf16_f32 v93, v100, v93
	global_store_dwordx4 v[102:103], v[90:93], off
	v_or_b32_e32 v94, 48, v150
	v_ashrrev_i32_e32 v95, 31, v94
	v_lshlrev_b64 v[94:95], 12, v[94:95]
	v_lshl_add_u64 v[94:95], v[94:95], 0, v[148:149]
	v_lshlrev_b64 v[94:95], 1, v[94:95]
	v_lshl_add_u64 v[96:97], s[50:51], 0, v[94:95]
	s_waitcnt vmcnt(15)
	v_lshlrev_b32_e32 v101, 16, v191
	v_and_b32_e32 v93, 0xffff0000, v191
	v_lshlrev_b32_e32 v98, 16, v188
	v_and_b32_e32 v90, 0xffff0000, v188
	v_lshlrev_b32_e32 v99, 16, v189
	v_and_b32_e32 v91, 0xffff0000, v189
	v_lshlrev_b32_e32 v100, 16, v190
	v_and_b32_e32 v92, 0xffff0000, v190
	v_mul_f32_e32 v85, v85, v93
	v_mul_f32_e32 v86, v86, v98
	v_mul_f32_e32 v87, v87, v90
	v_mul_f32_e32 v88, v88, v99
	v_mul_f32_e32 v89, v89, v91
	v_mul_f32_e32 v90, v82, v100
	v_mul_f32_e32 v91, v83, v92
	v_mul_f32_e32 v92, v84, v101
	v_cvt_pk_bf16_f32 v82, v86, v87
	v_cvt_pk_bf16_f32 v83, v88, v89
	v_cvt_pk_bf16_f32 v84, v90, v91
	v_cvt_pk_bf16_f32 v85, v92, v85
	global_store_dwordx4 v[102:103], v[82:85], off offset:256
	v_lshl_add_u64 v[86:87], s[20:21], 0, v[94:95]
	s_waitcnt vmcnt(15)
	v_lshlrev_b32_e32 v91, 16, v195
	v_and_b32_e32 v85, 0xffff0000, v195
	v_lshlrev_b32_e32 v88, 16, v192
	v_and_b32_e32 v82, 0xffff0000, v192
	v_lshlrev_b32_e32 v89, 16, v193
	v_and_b32_e32 v83, 0xffff0000, v193
	v_lshlrev_b32_e32 v90, 16, v194
	v_and_b32_e32 v84, 0xffff0000, v194
	v_mul_f32_e32 v77, v77, v85
	v_mul_f32_e32 v78, v78, v88
	v_mul_f32_e32 v79, v79, v82
	v_mul_f32_e32 v80, v80, v89
	v_mul_f32_e32 v81, v81, v83
	v_mul_f32_e32 v82, v74, v90
	v_mul_f32_e32 v83, v75, v84
	v_mul_f32_e32 v84, v76, v91
	v_cvt_pk_bf16_f32 v74, v78, v79
	v_cvt_pk_bf16_f32 v75, v80, v81
	v_cvt_pk_bf16_f32 v76, v82, v83
	v_cvt_pk_bf16_f32 v77, v84, v77
	global_store_dwordx4 v[86:87], v[74:77], off
	v_lshl_add_u64 v[78:79], v[146:147], 0, s[52:53]
	v_lshl_add_u64 v[80:81], s[50:51], 0, v[78:79]
	s_waitcnt vmcnt(15)
	v_lshlrev_b32_e32 v85, 16, v203
	v_and_b32_e32 v77, 0xffff0000, v203
	v_lshlrev_b32_e32 v82, 16, v200
	v_and_b32_e32 v74, 0xffff0000, v200
	v_lshlrev_b32_e32 v83, 16, v201
	v_and_b32_e32 v75, 0xffff0000, v201
	v_lshlrev_b32_e32 v84, 16, v202
	v_and_b32_e32 v76, 0xffff0000, v202
	v_mul_f32_e32 v69, v69, v77
	v_mul_f32_e32 v70, v70, v82
	v_mul_f32_e32 v71, v71, v74
	v_mul_f32_e32 v72, v72, v83
	v_mul_f32_e32 v73, v73, v75
	v_mul_f32_e32 v74, v66, v84
	v_mul_f32_e32 v75, v67, v76
	v_mul_f32_e32 v76, v68, v85
	v_cvt_pk_bf16_f32 v66, v70, v71
	v_cvt_pk_bf16_f32 v67, v72, v73
	v_cvt_pk_bf16_f32 v68, v74, v75
	v_cvt_pk_bf16_f32 v69, v76, v69
	global_store_dwordx4 v[86:87], v[66:69], off offset:256
	v_lshl_add_u64 v[70:71], s[20:21], 0, v[78:79]
	s_waitcnt vmcnt(15)
	v_lshlrev_b32_e32 v75, 16, v207
	v_and_b32_e32 v69, 0xffff0000, v207
	v_lshlrev_b32_e32 v72, 16, v204
	v_and_b32_e32 v66, 0xffff0000, v204
	v_lshlrev_b32_e32 v73, 16, v205
	v_and_b32_e32 v67, 0xffff0000, v205
	v_lshlrev_b32_e32 v74, 16, v206
	v_and_b32_e32 v68, 0xffff0000, v206
	v_mul_f32_e32 v61, v61, v69
	v_mul_f32_e32 v62, v62, v72
	v_mul_f32_e32 v63, v63, v66
	v_mul_f32_e32 v64, v64, v73
	v_mul_f32_e32 v65, v65, v67
	v_mul_f32_e32 v66, v58, v74
	v_mul_f32_e32 v67, v59, v68
	v_mul_f32_e32 v68, v60, v75
	v_cvt_pk_bf16_f32 v58, v62, v63
	v_cvt_pk_bf16_f32 v59, v64, v65
	v_cvt_pk_bf16_f32 v60, v66, v67
	v_cvt_pk_bf16_f32 v61, v68, v61
	global_store_dwordx4 v[70:71], v[58:61], off
	v_lshl_add_u64 v[62:63], v[146:147], 0, s[54:55]
	v_lshl_add_u64 v[64:65], s[50:51], 0, v[62:63]
	s_waitcnt vmcnt(15)
; __device__ __forceinline__ float bf_lo(unsigned w) { return __uint_as_float(w << 16); }
; __device__ __forceinline__ float bf_hi(unsigned w) { return __uint_as_float(w & 0xffff0000u); }
; __device__ __forceinline__ v4u pack8(f32x4 a, f32x4 b) { v4u w; w.x = cvt_pk_bf16(a[0], a[1]); w.y = cvt_pk_bf16(a[2], a[3]); w.z = cvt_pk_bf16(b[0], b[1]); w.w = cvt_pk_bf16(b[2], b[3]); return w; }
;     __device__ __forceinline__ void operator()(const f32x4 (&acc)[2][2][4][2], const Unit& u, int wr, int wc, int fr, int fq) const {
;         const bf16* const SA = (const bf16*)(ws + WS_SA);
;         const int row0 = u.pm * 256 + wr * 64 + fr, col0 = u.pn * 256 + wc * 32 + 8 * fq;
; #pragma unroll
;         for (int ai = 0; ai < 2; ++ai)
; #pragma unroll
;             for (int m = 0; m < 4; ++m) { const size_t off = (size_t)(row0 + ai * 128 + m * 16) * DM + col0;
; #pragma unroll
;                 for (int bj = 0; bj < 2; ++bj) { const v4u g = *(const v4u*)(SA + off + bj * 128); const f32x4 a0 = acc[ai][bj][m][0], a1 = acc[ai][bj][m][1];
;                     const f32x4 y0 = {a0[0] * bf_lo(g.x), a0[1] * bf_hi(g.x), a0[2] * bf_lo(g.y), a0[3] * bf_hi(g.y)};
;                     const f32x4 y1 = {a1[0] * bf_lo(g.z), a1[1] * bf_hi(g.z), a1[2] * bf_lo(g.w), a1[3] * bf_hi(g.w)};
;                     *(v4u*)(P + off + bj * 128) = pack8(y0, y1); } }
;     }
	v_lshlrev_b32_e32 v69, 16, v211
	v_and_b32_e32 v61, 0xffff0000, v211
	v_lshlrev_b32_e32 v66, 16, v208
	v_and_b32_e32 v58, 0xffff0000, v208
	v_lshlrev_b32_e32 v67, 16, v209
	v_and_b32_e32 v59, 0xffff0000, v209
	v_lshlrev_b32_e32 v68, 16, v210
	v_and_b32_e32 v60, 0xffff0000, v210
	v_mul_f32_e32 v53, v53, v61
	v_mul_f32_e32 v54, v54, v66
	v_mul_f32_e32 v55, v55, v58
	v_mul_f32_e32 v56, v56, v67
	v_mul_f32_e32 v57, v57, v59
	v_mul_f32_e32 v58, v50, v68
	v_mul_f32_e32 v59, v51, v60
	v_mul_f32_e32 v60, v52, v69
	v_cvt_pk_bf16_f32 v50, v54, v55
	v_cvt_pk_bf16_f32 v51, v56, v57
	v_cvt_pk_bf16_f32 v52, v58, v59
	v_cvt_pk_bf16_f32 v53, v60, v53
	global_store_dwordx4 v[70:71], v[50:53], off offset:256
	v_lshl_add_u64 v[54:55], s[20:21], 0, v[62:63]
	s_waitcnt vmcnt(15)
	v_lshlrev_b32_e32 v59, 16, v215
	v_and_b32_e32 v53, 0xffff0000, v215
	v_lshlrev_b32_e32 v56, 16, v212
	v_and_b32_e32 v50, 0xffff0000, v212
	v_lshlrev_b32_e32 v57, 16, v213
	v_and_b32_e32 v51, 0xffff0000, v213
	v_lshlrev_b32_e32 v58, 16, v214
	v_and_b32_e32 v52, 0xffff0000, v214
	v_mul_f32_e32 v45, v45, v53
	v_mul_f32_e32 v46, v46, v56
	v_mul_f32_e32 v47, v47, v50
	v_mul_f32_e32 v48, v48, v57
	v_mul_f32_e32 v49, v49, v51
	v_mul_f32_e32 v50, v42, v58
	v_mul_f32_e32 v51, v43, v52
	v_mul_f32_e32 v52, v44, v59
	v_cvt_pk_bf16_f32 v42, v46, v47
	v_cvt_pk_bf16_f32 v43, v48, v49
	v_cvt_pk_bf16_f32 v44, v50, v51
	v_cvt_pk_bf16_f32 v45, v52, v45
	global_store_dwordx4 v[54:55], v[42:45], off
	v_lshl_add_u64 v[46:47], v[146:147], 0, s[56:57]
	v_lshl_add_u64 v[48:49], s[50:51], 0, v[46:47]
	s_waitcnt vmcnt(15)
	v_lshlrev_b32_e32 v53, 16, v219
	v_and_b32_e32 v45, 0xffff0000, v219
	v_lshlrev_b32_e32 v50, 16, v216
	v_and_b32_e32 v42, 0xffff0000, v216
	v_lshlrev_b32_e32 v51, 16, v217
	v_and_b32_e32 v43, 0xffff0000, v217
	v_lshlrev_b32_e32 v52, 16, v218
	v_and_b32_e32 v44, 0xffff0000, v218
	v_mul_f32_e32 v37, v37, v45
	v_mul_f32_e32 v38, v38, v50
	v_mul_f32_e32 v39, v39, v42
	v_mul_f32_e32 v40, v40, v51
	v_mul_f32_e32 v41, v41, v43
	v_mul_f32_e32 v42, v34, v52
	v_mul_f32_e32 v43, v35, v44
	v_mul_f32_e32 v44, v36, v53
	v_cvt_pk_bf16_f32 v34, v38, v39
	v_cvt_pk_bf16_f32 v35, v40, v41
	v_cvt_pk_bf16_f32 v36, v42, v43
	v_cvt_pk_bf16_f32 v37, v44, v37
	global_store_dwordx4 v[54:55], v[34:37], off offset:256
	v_lshl_add_u64 v[38:39], s[20:21], 0, v[46:47]
	s_waitcnt vmcnt(15)
	v_lshlrev_b32_e32 v43, 16, v223
	v_and_b32_e32 v37, 0xffff0000, v223
	v_lshlrev_b32_e32 v40, 16, v220
	v_and_b32_e32 v34, 0xffff0000, v220
	v_lshlrev_b32_e32 v41, 16, v221
	v_and_b32_e32 v35, 0xffff0000, v221
	v_lshlrev_b32_e32 v42, 16, v222
	v_and_b32_e32 v36, 0xffff0000, v222
	v_mul_f32_e32 v29, v29, v37
	v_mul_f32_e32 v30, v30, v40
	v_mul_f32_e32 v31, v31, v34
	v_mul_f32_e32 v32, v32, v41
	v_mul_f32_e32 v33, v33, v35
	v_mul_f32_e32 v34, v26, v42
	v_mul_f32_e32 v35, v27, v36
	v_mul_f32_e32 v36, v28, v43
	v_cvt_pk_bf16_f32 v26, v30, v31
	v_cvt_pk_bf16_f32 v27, v32, v33
	v_cvt_pk_bf16_f32 v28, v34, v35
	v_cvt_pk_bf16_f32 v29, v36, v29
	global_store_dwordx4 v[38:39], v[26:29], off
	v_lshl_add_u64 v[30:31], v[146:147], 0, s[58:59]
	v_lshl_add_u64 v[32:33], s[50:51], 0, v[30:31]
	s_waitcnt vmcnt(15)
	v_lshlrev_b32_e32 v37, 16, v227
	v_and_b32_e32 v29, 0xffff0000, v227
	v_lshlrev_b32_e32 v34, 16, v224
	v_and_b32_e32 v26, 0xffff0000, v224
	v_lshlrev_b32_e32 v35, 16, v225
	v_and_b32_e32 v27, 0xffff0000, v225
	v_lshlrev_b32_e32 v36, 16, v226
	v_and_b32_e32 v28, 0xffff0000, v226
	v_mul_f32_e32 v21, v21, v29
	v_mul_f32_e32 v22, v22, v34
	v_mul_f32_e32 v23, v23, v26
	v_mul_f32_e32 v24, v24, v35
	v_mul_f32_e32 v25, v25, v27
	v_mul_f32_e32 v26, v18, v36
	v_mul_f32_e32 v27, v19, v28
	v_mul_f32_e32 v28, v20, v37
	v_cvt_pk_bf16_f32 v18, v22, v23
	v_cvt_pk_bf16_f32 v19, v24, v25
	v_cvt_pk_bf16_f32 v20, v26, v27
	v_cvt_pk_bf16_f32 v21, v28, v21
	global_store_dwordx4 v[38:39], v[18:21], off offset:256
	v_lshl_add_u64 v[22:23], s[20:21], 0, v[30:31]
	s_waitcnt vmcnt(15)
	v_lshlrev_b32_e32 v27, 16, v231
	v_and_b32_e32 v21, 0xffff0000, v231
	v_lshlrev_b32_e32 v24, 16, v228
	v_and_b32_e32 v18, 0xffff0000, v228
	v_lshlrev_b32_e32 v25, 16, v229
	v_and_b32_e32 v19, 0xffff0000, v229
	v_lshlrev_b32_e32 v26, 16, v230
	v_and_b32_e32 v20, 0xffff0000, v230
	v_mul_f32_e32 v13, v13, v21
	v_mul_f32_e32 v14, v14, v24
	v_mul_f32_e32 v15, v15, v18
	v_mul_f32_e32 v16, v16, v25
	v_mul_f32_e32 v17, v17, v19
	v_mul_f32_e32 v18, v10, v26
	v_mul_f32_e32 v19, v11, v20
	v_mul_f32_e32 v20, v12, v27
	v_cvt_pk_bf16_f32 v10, v14, v15
	v_cvt_pk_bf16_f32 v11, v16, v17
	v_cvt_pk_bf16_f32 v12, v18, v19
	v_cvt_pk_bf16_f32 v13, v20, v13
	global_store_dwordx4 v[22:23], v[10:13], off
	s_waitcnt vmcnt(15)
	v_lshlrev_b32_e32 v17, 16, v243
	v_and_b32_e32 v13, 0xffff0000, v243
	v_lshlrev_b32_e32 v14, 16, v240
	v_and_b32_e32 v10, 0xffff0000, v240
	v_lshlrev_b32_e32 v15, 16, v241
	v_and_b32_e32 v11, 0xffff0000, v241
	v_lshlrev_b32_e32 v16, 16, v242
	v_and_b32_e32 v12, 0xffff0000, v242
	v_mul_f32_e32 v5, v5, v13
	v_mul_f32_e32 v6, v6, v14
	v_mul_f32_e32 v7, v7, v10
	v_mul_f32_e32 v8, v8, v15
	v_mul_f32_e32 v9, v9, v11
	v_mul_f32_e32 v10, v2, v16
	v_mul_f32_e32 v11, v3, v12
	v_mul_f32_e32 v12, v4, v17
	v_cvt_pk_bf16_f32 v2, v6, v7
	v_cvt_pk_bf16_f32 v3, v8, v9
	v_cvt_pk_bf16_f32 v4, v10, v11
	v_cvt_pk_bf16_f32 v5, v12, v5
	global_store_dwordx4 v[22:23], v[2:5], off offset:256
	s_cbranch_vccnz .LBB0_1058
	s_andn2_b64 vcc, exec, s[8:9]
	s_cbranch_vccnz .LBB0_1057
	s_barrier
	s_branch .LBB0_1057

; __device__ __forceinline__ float bf_lo(unsigned w) { return __uint_as_float(w << 16); }
; __device__ __forceinline__ float bf_hi(unsigned w) { return __uint_as_float(w & 0xffff0000u); }
; __device__ __forceinline__ v4u pack8(f32x4 a, f32x4 b) { v4u w; w.x = cvt_pk_bf16(a[0], a[1]); w.y = cvt_pk_bf16(a[2], a[3]); w.z = cvt_pk_bf16(b[0], b[1]); w.w = cvt_pk_bf16(b[2], b[3]); return w; }
;     __device__ __forceinline__ void operator()(const f32x4 (&acc)[2][2][4][2], const Unit& u, int wr, int wc, int fr, int fq) const {
;         const bf16* const SB = (const bf16*)(ws + WS_SB); bf16* const Y = (bf16*)(ws + WS_H);
;         const int row0 = u.pm * 256 + wr * 64 + fr, col0 = u.pn * 256 + wc * 32 + 8 * fq;
; #pragma unroll
;         for (int ai = 0; ai < 2; ++ai)
; #pragma unroll
;             for (int m = 0; m < 4; ++m) { const size_t off = (size_t)(row0 + ai * 128 + m * 16) * DM + col0;
; #pragma unroll
;                 for (int bj = 0; bj < 2; ++bj) { const v4u g = *(const v4u*)(SB + off + bj * 128); const v4u p = *(const v4u*)(P + off + bj * 128);
;                     const f32x4 a0 = acc[ai][bj][m][0], a1 = acc[ai][bj][m][1];
;                     const f32x4 y0 = {bf_lo(p.x) + a0[0] * bf_lo(g.x), bf_hi(p.x) + a0[1] * bf_hi(g.x), bf_lo(p.y) + a0[2] * bf_lo(g.y), bf_hi(p.y) + a0[3] * bf_hi(g.y)};
;                     const f32x4 y1 = {bf_lo(p.z) + a1[0] * bf_lo(g.z), bf_hi(p.z) + a1[1] * bf_hi(g.z), bf_lo(p.w) + a1[2] * bf_lo(g.w), bf_hi(p.w) + a1[3] * bf_hi(g.w)};
;                     *(v4u*)(Y + off + bj * 128) = pack8(y0, y1); } }
;     }
.LBB0_1081:
	v_lshl_add_u32 v150, s64, 8, v152
	v_lshl_or_b32 v148, s41, 8, v154
	v_ashrrev_i32_e32 v151, 31, v150
	v_ashrrev_i32_e32 v149, 31, v148
	v_lshlrev_b64 v[146:147], 12, v[150:151]
	v_lshl_add_u64 v[146:147], v[146:147], 0, v[148:149]
	v_lshlrev_b64 v[146:147], 1, v[146:147]
	v_lshl_add_u64 v[172:173], s[20:21], 0, v[146:147]
	v_lshl_add_u64 v[162:163], s[46:47], 0, v[146:147]
	global_load_dwordx4 v[158:161], v[172:173], off
	global_load_dwordx4 v[180:183], v[162:163], off
	global_load_dwordx4 v[184:187], v[162:163], off offset:256
	global_load_dwordx4 v[188:191], v[172:173], off offset:256
	v_or_b32_e32 v232, 16, v150
	v_ashrrev_i32_e32 v233, 31, v232
	v_lshlrev_b64 v[232:233], 12, v[232:233]
	v_lshl_add_u64 v[232:233], v[232:233], 0, v[148:149]
	v_lshlrev_b64 v[232:233], 1, v[232:233]
	v_lshl_add_u64 v[250:251], s[20:21], 0, v[232:233]
	global_load_dwordx4 v[192:195], v[250:251], off
	v_or_b32_e32 v232, 16, v150
	v_ashrrev_i32_e32 v233, 31, v232
	v_lshlrev_b64 v[232:233], 12, v[232:233]
	v_lshl_add_u64 v[232:233], v[232:233], 0, v[148:149]
	v_lshlrev_b64 v[232:233], 1, v[232:233]
	v_lshl_add_u64 v[250:251], s[46:47], 0, v[232:233]
	global_load_dwordx4 v[200:203], v[250:251], off
	v_or_b32_e32 v232, 16, v150
	v_ashrrev_i32_e32 v233, 31, v232
	v_lshlrev_b64 v[232:233], 12, v[232:233]
	v_lshl_add_u64 v[232:233], v[232:233], 0, v[148:149]
	v_lshlrev_b64 v[232:233], 1, v[232:233]
	v_lshl_add_u64 v[250:251], s[46:47], 0, v[232:233]
	global_load_dwordx4 v[204:207], v[250:251], off offset:256
	v_or_b32_e32 v232, 16, v150
	v_ashrrev_i32_e32 v233, 31, v232
	v_lshlrev_b64 v[232:233], 12, v[232:233]
	v_lshl_add_u64 v[232:233], v[232:233], 0, v[148:149]
	v_lshlrev_b64 v[232:233], 1, v[232:233]
	v_lshl_add_u64 v[250:251], s[20:21], 0, v[232:233]
	global_load_dwordx4 v[208:211], v[250:251], off offset:256
	v_or_b32_e32 v232, 32, v150
	v_ashrrev_i32_e32 v233, 31, v232
	v_lshlrev_b64 v[232:233], 12, v[232:233]
	v_lshl_add_u64 v[232:233], v[232:233], 0, v[148:149]
	v_lshlrev_b64 v[232:233], 1, v[232:233]
	v_lshl_add_u64 v[250:251], s[20:21], 0, v[232:233]
	global_load_dwordx4 v[212:215], v[250:251], off
	v_or_b32_e32 v232, 32, v150
	v_ashrrev_i32_e32 v233, 31, v232
	v_lshlrev_b64 v[232:233], 12, v[232:233]
	v_lshl_add_u64 v[232:233], v[232:233], 0, v[148:149]
	v_lshlrev_b64 v[232:233], 1, v[232:233]
	v_lshl_add_u64 v[250:251], s[46:47], 0, v[232:233]
	global_load_dwordx4 v[216:219], v[250:251], off
	v_or_b32_e32 v232, 32, v150
	v_ashrrev_i32_e32 v233, 31, v232
	v_lshlrev_b64 v[232:233], 12, v[232:233]
	v_lshl_add_u64 v[232:233], v[232:233], 0, v[148:149]
	v_lshlrev_b64 v[232:233], 1, v[232:233]
	v_lshl_add_u64 v[250:251], s[46:47], 0, v[232:233]
	global_load_dwordx4 v[220:223], v[250:251], off offset:256
	v_or_b32_e32 v232, 32, v150
	v_ashrrev_i32_e32 v233, 31, v232
	v_lshlrev_b64 v[232:233], 12, v[232:233]
	v_lshl_add_u64 v[232:233], v[232:233], 0, v[148:149]
	v_lshlrev_b64 v[232:233], 1, v[232:233]
	v_lshl_add_u64 v[250:251], s[20:21], 0, v[232:233]
	global_load_dwordx4 v[224:227], v[250:251], off offset:256
	v_or_b32_e32 v232, 48, v150
	v_ashrrev_i32_e32 v233, 31, v232
	v_lshlrev_b64 v[232:233], 12, v[232:233]
	v_lshl_add_u64 v[232:233], v[232:233], 0, v[148:149]
	v_lshlrev_b64 v[232:233], 1, v[232:233]
	v_lshl_add_u64 v[250:251], s[20:21], 0, v[232:233]
	global_load_dwordx4 v[228:231], v[250:251], off
	v_or_b32_e32 v232, 48, v150
	v_ashrrev_i32_e32 v233, 31, v232
	v_lshlrev_b64 v[232:233], 12, v[232:233]
	v_lshl_add_u64 v[232:233], v[232:233], 0, v[148:149]
	v_lshlrev_b64 v[232:233], 1, v[232:233]
	v_lshl_add_u64 v[250:251], s[46:47], 0, v[232:233]
	global_load_dwordx4 v[240:243], v[250:251], off
	v_or_b32_e32 v232, 48, v150
	v_ashrrev_i32_e32 v233, 31, v232
	v_lshlrev_b64 v[232:233], 12, v[232:233]
	v_lshl_add_u64 v[232:233], v[232:233], 0, v[148:149]
	v_lshlrev_b64 v[232:233], 1, v[232:233]
	v_lshl_add_u64 v[250:251], s[46:47], 0, v[232:233]
	global_load_dwordx4 v[244:247], v[250:251], off offset:256
	s_andn2_b64 vcc, exec, s[4:5]
	s_mov_b64 s[4:5], -1
	s_waitcnt vmcnt(13)
	v_lshlrev_b32_e32 v151, 16, v158
	v_lshlrev_b32_e32 v166, 16, v180
	v_and_b32_e32 v158, 0xffff0000, v158
	v_and_b32_e32 v168, 0xffff0000, v180
	v_lshlrev_b32_e32 v174, 16, v159
	v_lshlrev_b32_e32 v175, 16, v181
	v_and_b32_e32 v159, 0xffff0000, v159
	v_and_b32_e32 v169, 0xffff0000, v181
	v_lshlrev_b32_e32 v176, 16, v160
	v_lshlrev_b32_e32 v177, 16, v182
	v_and_b32_e32 v160, 0xffff0000, v160
	v_and_b32_e32 v170, 0xffff0000, v182
	v_fmac_f32_e32 v158, v127, v168
	v_fmac_f32_e32 v159, v129, v169
	v_lshlrev_b32_e32 v178, 16, v161
	v_lshlrev_b32_e32 v179, 16, v183
	v_and_b32_e32 v161, 0xffff0000, v161
	v_and_b32_e32 v171, 0xffff0000, v183
	v_fmac_f32_e32 v151, v126, v166
	v_fmac_f32_e32 v174, v128, v175
	v_fmac_f32_e32 v176, v122, v177
	v_fmac_f32_e32 v160, v123, v170
	v_cvt_pk_bf16_f32 v122, v151, v158
	v_cvt_pk_bf16_f32 v123, v174, v159
	v_lshl_add_u64 v[158:159], s[36:37], 0, v[146:147]
	v_fmac_f32_e32 v178, v124, v179
	v_fmac_f32_e32 v161, v125, v171
	v_cvt_pk_bf16_f32 v124, v176, v160
	v_cvt_pk_bf16_f32 v125, v178, v161
	global_store_dwordx4 v[158:159], v[122:125], off
	v_or_b32_e32 v160, 16, v150
	v_ashrrev_i32_e32 v161, 31, v160
	v_lshlrev_b64 v[160:161], 12, v[160:161]
	v_lshl_add_u64 v[160:161], v[160:161], 0, v[148:149]
	v_lshlrev_b64 v[160:161], 1, v[160:161]
	v_lshl_add_u64 v[168:169], s[20:21], 0, v[160:161]
	v_lshl_add_u64 v[162:163], s[46:47], 0, v[160:161]
	s_waitcnt vmcnt(13)
	v_lshlrev_b32_e32 v151, 16, v184
	v_and_b32_e32 v126, 0xffff0000, v184
	v_lshlrev_b32_e32 v166, 16, v185
	v_and_b32_e32 v127, 0xffff0000, v185
	v_lshlrev_b32_e32 v170, 16, v186
	v_and_b32_e32 v128, 0xffff0000, v186
	v_lshlrev_b32_e32 v171, 16, v187
	v_and_b32_e32 v129, 0xffff0000, v187
	s_waitcnt vmcnt(12)
; __device__ __forceinline__ float bf_lo(unsigned w) { return __uint_as_float(w << 16); }
; __device__ __forceinline__ float bf_hi(unsigned w) { return __uint_as_float(w & 0xffff0000u); }
; __device__ __forceinline__ v4u pack8(f32x4 a, f32x4 b) { v4u w; w.x = cvt_pk_bf16(a[0], a[1]); w.y = cvt_pk_bf16(a[2], a[3]); w.z = cvt_pk_bf16(b[0], b[1]); w.w = cvt_pk_bf16(b[2], b[3]); return w; }
;     __device__ __forceinline__ void operator()(const f32x4 (&acc)[2][2][4][2], const Unit& u, int wr, int wc, int fr, int fq) const {
;         const bf16* const SB = (const bf16*)(ws + WS_SB); bf16* const Y = (bf16*)(ws + WS_H);
;         const int row0 = u.pm * 256 + wr * 64 + fr, col0 = u.pn * 256 + wc * 32 + 8 * fq;
; #pragma unroll
;         for (int ai = 0; ai < 2; ++ai)
; #pragma unroll
;             for (int m = 0; m < 4; ++m) { const size_t off = (size_t)(row0 + ai * 128 + m * 16) * DM + col0;
; #pragma unroll
;                 for (int bj = 0; bj < 2; ++bj) { const v4u g = *(const v4u*)(SB + off + bj * 128); const v4u p = *(const v4u*)(P + off + bj * 128);
;                     const f32x4 a0 = acc[ai][bj][m][0], a1 = acc[ai][bj][m][1];
;                     const f32x4 y0 = {bf_lo(p.x) + a0[0] * bf_lo(g.x), bf_hi(p.x) + a0[1] * bf_hi(g.x), bf_lo(p.y) + a0[2] * bf_lo(g.y), bf_hi(p.y) + a0[3] * bf_hi(g.y)};
;                     const f32x4 y1 = {bf_lo(p.z) + a1[0] * bf_lo(g.z), bf_hi(p.z) + a1[1] * bf_hi(g.z), bf_lo(p.w) + a1[2] * bf_lo(g.w), bf_hi(p.w) + a1[3] * bf_hi(g.w)};
;                     *(v4u*)(Y + off + bj * 128) = pack8(y0, y1); } }
;     }
	v_lshlrev_b32_e32 v172, 16, v188
	v_and_b32_e32 v122, 0xffff0000, v188
	v_lshlrev_b32_e32 v173, 16, v189
	v_and_b32_e32 v123, 0xffff0000, v189
	v_lshlrev_b32_e32 v174, 16, v190
	v_and_b32_e32 v124, 0xffff0000, v190
	v_lshlrev_b32_e32 v175, 16, v191
	v_and_b32_e32 v125, 0xffff0000, v191
	v_fmac_f32_e32 v172, v118, v151
	v_fmac_f32_e32 v122, v119, v126
	v_fmac_f32_e32 v173, v120, v166
	v_fmac_f32_e32 v123, v121, v127
	v_fmac_f32_e32 v174, v114, v170
	v_fmac_f32_e32 v124, v115, v128
	v_fmac_f32_e32 v175, v116, v171
	v_fmac_f32_e32 v125, v117, v129
	v_cvt_pk_bf16_f32 v114, v172, v122
	v_cvt_pk_bf16_f32 v115, v173, v123
	v_cvt_pk_bf16_f32 v116, v174, v124
	v_cvt_pk_bf16_f32 v117, v175, v125
	global_store_dwordx4 v[158:159], v[114:117], off offset:256
	s_nop 0
	s_waitcnt vmcnt(12)
	v_lshlrev_b32_e32 v122, 16, v192
	s_waitcnt vmcnt(11)
	v_lshlrev_b32_e32 v123, 16, v200
	v_and_b32_e32 v114, 0xffff0000, v192
	v_and_b32_e32 v118, 0xffff0000, v200
	v_lshlrev_b32_e32 v124, 16, v193
	v_lshlrev_b32_e32 v125, 16, v201
	v_and_b32_e32 v115, 0xffff0000, v193
	v_and_b32_e32 v119, 0xffff0000, v201
	v_lshlrev_b32_e32 v126, 16, v194
	v_lshlrev_b32_e32 v127, 16, v202
	v_and_b32_e32 v116, 0xffff0000, v194
	v_and_b32_e32 v120, 0xffff0000, v202
	v_fmac_f32_e32 v114, v111, v118
	v_fmac_f32_e32 v115, v113, v119
	v_lshlrev_b32_e32 v128, 16, v195
	v_lshlrev_b32_e32 v129, 16, v203
	v_and_b32_e32 v117, 0xffff0000, v195
	v_and_b32_e32 v121, 0xffff0000, v203
	v_fmac_f32_e32 v122, v110, v123
	v_fmac_f32_e32 v124, v112, v125
	v_fmac_f32_e32 v126, v106, v127
	v_fmac_f32_e32 v116, v107, v120
	v_cvt_pk_bf16_f32 v106, v122, v114
	v_cvt_pk_bf16_f32 v107, v124, v115
	v_lshl_add_u64 v[114:115], s[36:37], 0, v[160:161]
	v_fmac_f32_e32 v128, v108, v129
	v_fmac_f32_e32 v117, v109, v121
	v_cvt_pk_bf16_f32 v108, v126, v116
	v_cvt_pk_bf16_f32 v109, v128, v117
	global_store_dwordx4 v[114:115], v[106:109], off
	v_or_b32_e32 v116, 32, v150
	v_ashrrev_i32_e32 v117, 31, v116
	v_lshlrev_b64 v[116:117], 12, v[116:117]
	v_lshl_add_u64 v[116:117], v[116:117], 0, v[148:149]
	v_lshlrev_b64 v[116:117], 1, v[116:117]
	v_lshl_add_u64 v[120:121], s[20:21], 0, v[116:117]
	v_lshl_add_u64 v[118:119], s[46:47], 0, v[116:117]
	s_waitcnt vmcnt(11)
	v_lshlrev_b32_e32 v122, 16, v204
	v_and_b32_e32 v110, 0xffff0000, v204
	v_lshlrev_b32_e32 v123, 16, v205
	v_and_b32_e32 v111, 0xffff0000, v205
	v_lshlrev_b32_e32 v124, 16, v206
	v_and_b32_e32 v112, 0xffff0000, v206
	v_lshlrev_b32_e32 v125, 16, v207
	v_and_b32_e32 v113, 0xffff0000, v207
	s_waitcnt vmcnt(10)
	v_lshlrev_b32_e32 v126, 16, v208
	v_and_b32_e32 v106, 0xffff0000, v208
	v_lshlrev_b32_e32 v127, 16, v209
	v_and_b32_e32 v107, 0xffff0000, v209
	v_lshlrev_b32_e32 v128, 16, v210
	v_and_b32_e32 v108, 0xffff0000, v210
	v_lshlrev_b32_e32 v129, 16, v211
	v_and_b32_e32 v109, 0xffff0000, v211
	v_fmac_f32_e32 v126, v102, v122
	v_fmac_f32_e32 v106, v103, v110
	v_fmac_f32_e32 v127, v104, v123
	v_fmac_f32_e32 v107, v105, v111
	v_fmac_f32_e32 v128, v98, v124
	v_fmac_f32_e32 v108, v99, v112
	v_fmac_f32_e32 v129, v100, v125
	v_fmac_f32_e32 v109, v101, v113
	v_cvt_pk_bf16_f32 v98, v126, v106
	v_cvt_pk_bf16_f32 v99, v127, v107
	v_cvt_pk_bf16_f32 v100, v128, v108
	v_cvt_pk_bf16_f32 v101, v129, v109
	global_store_dwordx4 v[114:115], v[98:101], off offset:256
	s_nop 0
	s_waitcnt vmcnt(10)
	v_lshlrev_b32_e32 v106, 16, v212
	s_waitcnt vmcnt(9)
	v_lshlrev_b32_e32 v107, 16, v216
	v_and_b32_e32 v98, 0xffff0000, v212
	v_and_b32_e32 v102, 0xffff0000, v216
	v_lshlrev_b32_e32 v108, 16, v213
	v_lshlrev_b32_e32 v109, 16, v217
	v_and_b32_e32 v99, 0xffff0000, v213
	v_and_b32_e32 v103, 0xffff0000, v217
	v_lshlrev_b32_e32 v110, 16, v214
	v_lshlrev_b32_e32 v111, 16, v218
	v_and_b32_e32 v100, 0xffff0000, v214
	v_and_b32_e32 v104, 0xffff0000, v218
	v_fmac_f32_e32 v98, v95, v102
	v_fmac_f32_e32 v99, v97, v103
	v_lshlrev_b32_e32 v112, 16, v215
	v_lshlrev_b32_e32 v113, 16, v219
	v_and_b32_e32 v101, 0xffff0000, v215
	v_and_b32_e32 v105, 0xffff0000, v219
	v_fmac_f32_e32 v106, v94, v107
	v_fmac_f32_e32 v108, v96, v109
	v_fmac_f32_e32 v110, v90, v111
	v_fmac_f32_e32 v100, v91, v104
	v_cvt_pk_bf16_f32 v90, v106, v98
	v_cvt_pk_bf16_f32 v91, v108, v99
	v_lshl_add_u64 v[98:99], s[36:37], 0, v[116:117]
	v_fmac_f32_e32 v112, v92, v113
	v_fmac_f32_e32 v101, v93, v105
	v_cvt_pk_bf16_f32 v92, v110, v100
	v_cvt_pk_bf16_f32 v93, v112, v101
	global_store_dwordx4 v[98:99], v[90:93], off
	v_or_b32_e32 v100, 48, v150
	v_ashrrev_i32_e32 v101, 31, v100
	v_lshlrev_b64 v[100:101], 12, v[100:101]
	v_lshl_add_u64 v[100:101], v[100:101], 0, v[148:149]
	v_lshlrev_b64 v[100:101], 1, v[100:101]
	v_lshl_add_u64 v[104:105], s[20:21], 0, v[100:101]
	v_lshl_add_u64 v[102:103], s[46:47], 0, v[100:101]
	s_waitcnt vmcnt(9)
	v_lshlrev_b32_e32 v106, 16, v220
	v_and_b32_e32 v94, 0xffff0000, v220
	v_lshlrev_b32_e32 v107, 16, v221
	v_and_b32_e32 v95, 0xffff0000, v221
	v_lshlrev_b32_e32 v108, 16, v222
	v_and_b32_e32 v96, 0xffff0000, v222
	v_lshlrev_b32_e32 v109, 16, v223
	v_and_b32_e32 v97, 0xffff0000, v223
	s_waitcnt vmcnt(8)
	v_lshlrev_b32_e32 v110, 16, v224
	v_and_b32_e32 v90, 0xffff0000, v224
	v_lshlrev_b32_e32 v111, 16, v225
	v_and_b32_e32 v91, 0xffff0000, v225
	v_lshlrev_b32_e32 v112, 16, v226
	v_and_b32_e32 v92, 0xffff0000, v226
	v_lshlrev_b32_e32 v113, 16, v227
	v_and_b32_e32 v93, 0xffff0000, v227
	v_fmac_f32_e32 v110, v86, v106
	v_fmac_f32_e32 v90, v87, v94
	v_fmac_f32_e32 v111, v88, v107
	v_fmac_f32_e32 v91, v89, v95
	v_fmac_f32_e32 v112, v82, v108
	v_fmac_f32_e32 v92, v83, v96
	v_fmac_f32_e32 v113, v84, v109
	v_fmac_f32_e32 v93, v85, v97
	v_cvt_pk_bf16_f32 v82, v110, v90
	v_cvt_pk_bf16_f32 v83, v111, v91
	v_cvt_pk_bf16_f32 v84, v112, v92
	v_cvt_pk_bf16_f32 v85, v113, v93
	global_store_dwordx4 v[98:99], v[82:85], off offset:256
	s_nop 0
	s_waitcnt vmcnt(8)
; __device__ __forceinline__ float bf_lo(unsigned w) { return __uint_as_float(w << 16); }
; __device__ __forceinline__ float bf_hi(unsigned w) { return __uint_as_float(w & 0xffff0000u); }
; __device__ __forceinline__ v4u pack8(f32x4 a, f32x4 b) { v4u w; w.x = cvt_pk_bf16(a[0], a[1]); w.y = cvt_pk_bf16(a[2], a[3]); w.z = cvt_pk_bf16(b[0], b[1]); w.w = cvt_pk_bf16(b[2], b[3]); return w; }
;     __device__ __forceinline__ void operator()(const f32x4 (&acc)[2][2][4][2], const Unit& u, int wr, int wc, int fr, int fq) const {
;         const bf16* const SB = (const bf16*)(ws + WS_SB); bf16* const Y = (bf16*)(ws + WS_H);
;         const int row0 = u.pm * 256 + wr * 64 + fr, col0 = u.pn * 256 + wc * 32 + 8 * fq;
; #pragma unroll
;         for (int ai = 0; ai < 2; ++ai)
; #pragma unroll
;             for (int m = 0; m < 4; ++m) { const size_t off = (size_t)(row0 + ai * 128 + m * 16) * DM + col0;
; #pragma unroll
;                 for (int bj = 0; bj < 2; ++bj) { const v4u g = *(const v4u*)(SB + off + bj * 128); const v4u p = *(const v4u*)(P + off + bj * 128);
;                     const f32x4 a0 = acc[ai][bj][m][0], a1 = acc[ai][bj][m][1];
;                     const f32x4 y0 = {bf_lo(p.x) + a0[0] * bf_lo(g.x), bf_hi(p.x) + a0[1] * bf_hi(g.x), bf_lo(p.y) + a0[2] * bf_lo(g.y), bf_hi(p.y) + a0[3] * bf_hi(g.y)};
;                     const f32x4 y1 = {bf_lo(p.z) + a1[0] * bf_lo(g.z), bf_hi(p.z) + a1[1] * bf_hi(g.z), bf_lo(p.w) + a1[2] * bf_lo(g.w), bf_hi(p.w) + a1[3] * bf_hi(g.w)};
;                     *(v4u*)(Y + off + bj * 128) = pack8(y0, y1); } }
;     }
	v_lshlrev_b32_e32 v90, 16, v228
	s_waitcnt vmcnt(7)
	v_lshlrev_b32_e32 v91, 16, v240
	v_and_b32_e32 v82, 0xffff0000, v228
	v_and_b32_e32 v86, 0xffff0000, v240
	v_lshlrev_b32_e32 v92, 16, v229
	v_lshlrev_b32_e32 v93, 16, v241
	v_and_b32_e32 v83, 0xffff0000, v229
	v_and_b32_e32 v87, 0xffff0000, v241
	v_lshlrev_b32_e32 v94, 16, v230
	v_lshlrev_b32_e32 v95, 16, v242
	v_and_b32_e32 v84, 0xffff0000, v230
	v_and_b32_e32 v88, 0xffff0000, v242
	v_fmac_f32_e32 v82, v79, v86
	v_fmac_f32_e32 v83, v81, v87
	v_lshlrev_b32_e32 v96, 16, v231
	v_lshlrev_b32_e32 v97, 16, v243
	v_and_b32_e32 v85, 0xffff0000, v231
	v_and_b32_e32 v89, 0xffff0000, v243
	v_fmac_f32_e32 v90, v78, v91
	v_fmac_f32_e32 v92, v80, v93
	v_fmac_f32_e32 v94, v74, v95
	v_fmac_f32_e32 v84, v75, v88
	v_cvt_pk_bf16_f32 v74, v90, v82
	v_cvt_pk_bf16_f32 v75, v92, v83
	v_lshl_add_u64 v[82:83], s[36:37], 0, v[100:101]
	v_fmac_f32_e32 v96, v76, v97
	v_fmac_f32_e32 v85, v77, v89
	v_cvt_pk_bf16_f32 v76, v94, v84
	v_cvt_pk_bf16_f32 v77, v96, v85
	global_store_dwordx4 v[82:83], v[74:77], off
	v_lshl_add_u64 v[84:85], v[146:147], 0, s[48:49]
	global_load_dwordx4 v[74:77], v[104:105], off offset:256
	v_lshl_add_u64 v[88:89], s[20:21], 0, v[84:85]
	v_lshl_add_u64 v[86:87], s[46:47], 0, v[84:85]
	s_waitcnt vmcnt(8)
	v_lshlrev_b32_e32 v90, 16, v244
	v_and_b32_e32 v78, 0xffff0000, v244
	v_lshlrev_b32_e32 v91, 16, v245
	v_and_b32_e32 v79, 0xffff0000, v245
	v_lshlrev_b32_e32 v92, 16, v246
	v_and_b32_e32 v80, 0xffff0000, v246
	v_lshlrev_b32_e32 v93, 16, v247
	v_and_b32_e32 v81, 0xffff0000, v247
	global_load_dwordx4 v[180:183], v[88:89], off
	global_load_dwordx4 v[184:187], v[86:87], off
	global_load_dwordx4 v[188:191], v[86:87], off offset:256
	global_load_dwordx4 v[192:195], v[88:89], off offset:256
	v_lshl_add_u64 v[232:233], v[146:147], 0, s[50:51]
	v_lshl_add_u64 v[250:251], s[20:21], 0, v[232:233]
	global_load_dwordx4 v[200:203], v[250:251], off
	v_lshl_add_u64 v[232:233], v[146:147], 0, s[50:51]
	v_lshl_add_u64 v[250:251], s[46:47], 0, v[232:233]
	global_load_dwordx4 v[204:207], v[250:251], off
	v_lshl_add_u64 v[232:233], v[146:147], 0, s[50:51]
	v_lshl_add_u64 v[250:251], s[46:47], 0, v[232:233]
	global_load_dwordx4 v[208:211], v[250:251], off offset:256
	v_lshl_add_u64 v[232:233], v[146:147], 0, s[50:51]
	v_lshl_add_u64 v[250:251], s[20:21], 0, v[232:233]
	global_load_dwordx4 v[212:215], v[250:251], off offset:256
	v_lshl_add_u64 v[232:233], v[146:147], 0, s[52:53]
	v_lshl_add_u64 v[250:251], s[20:21], 0, v[232:233]
	global_load_dwordx4 v[216:219], v[250:251], off
	v_lshl_add_u64 v[232:233], v[146:147], 0, s[52:53]
	v_lshl_add_u64 v[250:251], s[46:47], 0, v[232:233]
	global_load_dwordx4 v[220:223], v[250:251], off
	v_lshl_add_u64 v[232:233], v[146:147], 0, s[52:53]
	v_lshl_add_u64 v[250:251], s[46:47], 0, v[232:233]
	global_load_dwordx4 v[224:227], v[250:251], off offset:256
	v_lshl_add_u64 v[232:233], v[146:147], 0, s[52:53]
	v_lshl_add_u64 v[250:251], s[20:21], 0, v[232:233]
	global_load_dwordx4 v[228:231], v[250:251], off offset:256
	v_lshl_add_u64 v[232:233], v[146:147], 0, s[54:55]
	v_lshl_add_u64 v[250:251], s[20:21], 0, v[232:233]
	global_load_dwordx4 v[240:243], v[250:251], off
	v_lshl_add_u64 v[232:233], v[146:147], 0, s[54:55]
	v_lshl_add_u64 v[250:251], s[46:47], 0, v[232:233]
	global_load_dwordx4 v[244:247], v[250:251], off
	s_waitcnt vmcnt(14)
	v_lshlrev_b32_e32 v94, 16, v74
	v_and_b32_e32 v74, 0xffff0000, v74
	v_lshlrev_b32_e32 v95, 16, v75
	v_and_b32_e32 v75, 0xffff0000, v75
	v_lshlrev_b32_e32 v96, 16, v76
	v_and_b32_e32 v76, 0xffff0000, v76
	v_lshlrev_b32_e32 v97, 16, v77
	v_and_b32_e32 v77, 0xffff0000, v77
	v_fmac_f32_e32 v94, v70, v90
	v_fmac_f32_e32 v74, v71, v78
	v_fmac_f32_e32 v95, v72, v91
	v_fmac_f32_e32 v75, v73, v79
	v_fmac_f32_e32 v96, v66, v92
	v_fmac_f32_e32 v76, v67, v80
	v_fmac_f32_e32 v97, v68, v93
	v_fmac_f32_e32 v77, v69, v81
	v_cvt_pk_bf16_f32 v66, v94, v74
	v_cvt_pk_bf16_f32 v67, v95, v75
	v_cvt_pk_bf16_f32 v68, v96, v76
	v_cvt_pk_bf16_f32 v69, v97, v77
	global_store_dwordx4 v[82:83], v[66:69], off offset:256
	s_nop 0
	s_waitcnt vmcnt(14)
	v_lshlrev_b32_e32 v74, 16, v180
	s_waitcnt vmcnt(13)
	v_lshlrev_b32_e32 v75, 16, v184
	v_and_b32_e32 v66, 0xffff0000, v180
	v_and_b32_e32 v70, 0xffff0000, v184
	v_lshlrev_b32_e32 v76, 16, v181
	v_lshlrev_b32_e32 v77, 16, v185
	v_and_b32_e32 v67, 0xffff0000, v181
	v_and_b32_e32 v71, 0xffff0000, v185
	v_lshlrev_b32_e32 v78, 16, v182
	v_lshlrev_b32_e32 v79, 16, v186
	v_and_b32_e32 v68, 0xffff0000, v182
	v_and_b32_e32 v72, 0xffff0000, v186
	v_fmac_f32_e32 v66, v63, v70
	v_fmac_f32_e32 v67, v65, v71
	v_lshlrev_b32_e32 v80, 16, v183
	v_lshlrev_b32_e32 v81, 16, v187
	v_and_b32_e32 v69, 0xffff0000, v183
	v_and_b32_e32 v73, 0xffff0000, v187
	v_fmac_f32_e32 v74, v62, v75
	v_fmac_f32_e32 v76, v64, v77
	v_fmac_f32_e32 v78, v58, v79
	v_fmac_f32_e32 v68, v59, v72
	v_cvt_pk_bf16_f32 v58, v74, v66
	v_cvt_pk_bf16_f32 v59, v76, v67
	v_lshl_add_u64 v[66:67], s[36:37], 0, v[84:85]
	v_fmac_f32_e32 v80, v60, v81
	v_fmac_f32_e32 v69, v61, v73
	v_cvt_pk_bf16_f32 v60, v78, v68
	v_cvt_pk_bf16_f32 v61, v80, v69
	global_store_dwordx4 v[66:67], v[58:61], off
	v_lshl_add_u64 v[68:69], v[146:147], 0, s[50:51]
	v_lshl_add_u64 v[72:73], s[20:21], 0, v[68:69]
	v_lshl_add_u64 v[70:71], s[46:47], 0, v[68:69]
	s_waitcnt vmcnt(13)
	v_lshlrev_b32_e32 v74, 16, v188
	v_and_b32_e32 v62, 0xffff0000, v188
	v_lshlrev_b32_e32 v75, 16, v189
	v_and_b32_e32 v63, 0xffff0000, v189
	v_lshlrev_b32_e32 v76, 16, v190
	v_and_b32_e32 v64, 0xffff0000, v190
	v_lshlrev_b32_e32 v77, 16, v191
	v_and_b32_e32 v65, 0xffff0000, v191
	s_waitcnt vmcnt(12)
; __device__ __forceinline__ float bf_lo(unsigned w) { return __uint_as_float(w << 16); }
; __device__ __forceinline__ float bf_hi(unsigned w) { return __uint_as_float(w & 0xffff0000u); }
; __device__ __forceinline__ v4u pack8(f32x4 a, f32x4 b) { v4u w; w.x = cvt_pk_bf16(a[0], a[1]); w.y = cvt_pk_bf16(a[2], a[3]); w.z = cvt_pk_bf16(b[0], b[1]); w.w = cvt_pk_bf16(b[2], b[3]); return w; }
;     __device__ __forceinline__ void operator()(const f32x4 (&acc)[2][2][4][2], const Unit& u, int wr, int wc, int fr, int fq) const {
;         const bf16* const SB = (const bf16*)(ws + WS_SB); bf16* const Y = (bf16*)(ws + WS_H);
;         const int row0 = u.pm * 256 + wr * 64 + fr, col0 = u.pn * 256 + wc * 32 + 8 * fq;
; #pragma unroll
;         for (int ai = 0; ai < 2; ++ai)
; #pragma unroll
;             for (int m = 0; m < 4; ++m) { const size_t off = (size_t)(row0 + ai * 128 + m * 16) * DM + col0;
; #pragma unroll
;                 for (int bj = 0; bj < 2; ++bj) { const v4u g = *(const v4u*)(SB + off + bj * 128); const v4u p = *(const v4u*)(P + off + bj * 128);
;                     const f32x4 a0 = acc[ai][bj][m][0], a1 = acc[ai][bj][m][1];
;                     const f32x4 y0 = {bf_lo(p.x) + a0[0] * bf_lo(g.x), bf_hi(p.x) + a0[1] * bf_hi(g.x), bf_lo(p.y) + a0[2] * bf_lo(g.y), bf_hi(p.y) + a0[3] * bf_hi(g.y)};
;                     const f32x4 y1 = {bf_lo(p.z) + a1[0] * bf_lo(g.z), bf_hi(p.z) + a1[1] * bf_hi(g.z), bf_lo(p.w) + a1[2] * bf_lo(g.w), bf_hi(p.w) + a1[3] * bf_hi(g.w)};
;                     *(v4u*)(Y + off + bj * 128) = pack8(y0, y1); } }
;     }
	v_lshlrev_b32_e32 v78, 16, v192
	v_and_b32_e32 v58, 0xffff0000, v192
	v_lshlrev_b32_e32 v79, 16, v193
	v_and_b32_e32 v59, 0xffff0000, v193
	v_lshlrev_b32_e32 v80, 16, v194
	v_and_b32_e32 v60, 0xffff0000, v194
	v_lshlrev_b32_e32 v81, 16, v195
	v_and_b32_e32 v61, 0xffff0000, v195
	v_fmac_f32_e32 v78, v54, v74
	v_fmac_f32_e32 v58, v55, v62
	v_fmac_f32_e32 v79, v56, v75
	v_fmac_f32_e32 v59, v57, v63
	v_fmac_f32_e32 v80, v50, v76
	v_fmac_f32_e32 v60, v51, v64
	v_fmac_f32_e32 v81, v52, v77
	v_fmac_f32_e32 v61, v53, v65
	v_cvt_pk_bf16_f32 v50, v78, v58
	v_cvt_pk_bf16_f32 v51, v79, v59
	v_cvt_pk_bf16_f32 v52, v80, v60
	v_cvt_pk_bf16_f32 v53, v81, v61
	global_store_dwordx4 v[66:67], v[50:53], off offset:256
	s_nop 0
	s_waitcnt vmcnt(12)
	v_lshlrev_b32_e32 v58, 16, v200
	s_waitcnt vmcnt(11)
	v_lshlrev_b32_e32 v59, 16, v204
	v_and_b32_e32 v50, 0xffff0000, v200
	v_and_b32_e32 v54, 0xffff0000, v204
	v_lshlrev_b32_e32 v60, 16, v201
	v_lshlrev_b32_e32 v61, 16, v205
	v_and_b32_e32 v51, 0xffff0000, v201
	v_and_b32_e32 v55, 0xffff0000, v205
	v_lshlrev_b32_e32 v62, 16, v202
	v_lshlrev_b32_e32 v63, 16, v206
	v_and_b32_e32 v52, 0xffff0000, v202
	v_and_b32_e32 v56, 0xffff0000, v206
	v_fmac_f32_e32 v50, v47, v54
	v_fmac_f32_e32 v51, v49, v55
	v_lshlrev_b32_e32 v64, 16, v203
	v_lshlrev_b32_e32 v65, 16, v207
	v_and_b32_e32 v53, 0xffff0000, v203
	v_and_b32_e32 v57, 0xffff0000, v207
	v_fmac_f32_e32 v58, v46, v59
	v_fmac_f32_e32 v60, v48, v61
	v_fmac_f32_e32 v62, v42, v63
	v_fmac_f32_e32 v52, v43, v56
	v_cvt_pk_bf16_f32 v42, v58, v50
	v_cvt_pk_bf16_f32 v43, v60, v51
	v_lshl_add_u64 v[50:51], s[36:37], 0, v[68:69]
	v_fmac_f32_e32 v64, v44, v65
	v_fmac_f32_e32 v53, v45, v57
	v_cvt_pk_bf16_f32 v44, v62, v52
	v_cvt_pk_bf16_f32 v45, v64, v53
	global_store_dwordx4 v[50:51], v[42:45], off
	v_lshl_add_u64 v[52:53], v[146:147], 0, s[52:53]
	v_lshl_add_u64 v[56:57], s[20:21], 0, v[52:53]
	v_lshl_add_u64 v[54:55], s[46:47], 0, v[52:53]
	s_waitcnt vmcnt(11)
	v_lshlrev_b32_e32 v58, 16, v208
	v_and_b32_e32 v46, 0xffff0000, v208
	v_lshlrev_b32_e32 v59, 16, v209
	v_and_b32_e32 v47, 0xffff0000, v209
	v_lshlrev_b32_e32 v60, 16, v210
	v_and_b32_e32 v48, 0xffff0000, v210
	v_lshlrev_b32_e32 v61, 16, v211
	v_and_b32_e32 v49, 0xffff0000, v211
	s_waitcnt vmcnt(10)
	v_lshlrev_b32_e32 v62, 16, v212
	v_and_b32_e32 v42, 0xffff0000, v212
	v_lshlrev_b32_e32 v63, 16, v213
	v_and_b32_e32 v43, 0xffff0000, v213
	v_lshlrev_b32_e32 v64, 16, v214
	v_and_b32_e32 v44, 0xffff0000, v214
	v_lshlrev_b32_e32 v65, 16, v215
	v_and_b32_e32 v45, 0xffff0000, v215
	v_fmac_f32_e32 v62, v38, v58
	v_fmac_f32_e32 v42, v39, v46
	v_fmac_f32_e32 v63, v40, v59
	v_fmac_f32_e32 v43, v41, v47
	v_fmac_f32_e32 v64, v34, v60
	v_fmac_f32_e32 v44, v35, v48
	v_fmac_f32_e32 v65, v36, v61
	v_fmac_f32_e32 v45, v37, v49
	v_cvt_pk_bf16_f32 v34, v62, v42
	v_cvt_pk_bf16_f32 v35, v63, v43
	v_cvt_pk_bf16_f32 v36, v64, v44
	v_cvt_pk_bf16_f32 v37, v65, v45
	global_store_dwordx4 v[50:51], v[34:37], off offset:256
	s_nop 0
	s_waitcnt vmcnt(10)
	v_lshlrev_b32_e32 v42, 16, v216
	s_waitcnt vmcnt(9)
	v_lshlrev_b32_e32 v43, 16, v220
	v_and_b32_e32 v34, 0xffff0000, v216
	v_and_b32_e32 v38, 0xffff0000, v220
	v_lshlrev_b32_e32 v44, 16, v217
	v_lshlrev_b32_e32 v45, 16, v221
	v_and_b32_e32 v35, 0xffff0000, v217
	v_and_b32_e32 v39, 0xffff0000, v221
	v_lshlrev_b32_e32 v46, 16, v218
	v_lshlrev_b32_e32 v47, 16, v222
	v_and_b32_e32 v36, 0xffff0000, v218
	v_and_b32_e32 v40, 0xffff0000, v222
	v_fmac_f32_e32 v34, v31, v38
	v_fmac_f32_e32 v35, v33, v39
	v_lshlrev_b32_e32 v48, 16, v219
	v_lshlrev_b32_e32 v49, 16, v223
	v_and_b32_e32 v37, 0xffff0000, v219
	v_and_b32_e32 v41, 0xffff0000, v223
	v_fmac_f32_e32 v42, v30, v43
	v_fmac_f32_e32 v44, v32, v45
	v_fmac_f32_e32 v46, v26, v47
	v_fmac_f32_e32 v36, v27, v40
	v_cvt_pk_bf16_f32 v26, v42, v34
	v_cvt_pk_bf16_f32 v27, v44, v35
	v_lshl_add_u64 v[34:35], s[36:37], 0, v[52:53]
	v_fmac_f32_e32 v48, v28, v49
	v_fmac_f32_e32 v37, v29, v41
	v_cvt_pk_bf16_f32 v28, v46, v36
	v_cvt_pk_bf16_f32 v29, v48, v37
	global_store_dwordx4 v[34:35], v[26:29], off
	v_lshl_add_u64 v[36:37], v[146:147], 0, s[54:55]
	v_lshl_add_u64 v[40:41], s[20:21], 0, v[36:37]
	v_lshl_add_u64 v[38:39], s[46:47], 0, v[36:37]
	s_waitcnt vmcnt(9)
; __device__ __forceinline__ float bf_lo(unsigned w) { return __uint_as_float(w << 16); }
; __device__ __forceinline__ float bf_hi(unsigned w) { return __uint_as_float(w & 0xffff0000u); }
; __device__ __forceinline__ v4u pack8(f32x4 a, f32x4 b) { v4u w; w.x = cvt_pk_bf16(a[0], a[1]); w.y = cvt_pk_bf16(a[2], a[3]); w.z = cvt_pk_bf16(b[0], b[1]); w.w = cvt_pk_bf16(b[2], b[3]); return w; }
;     __device__ __forceinline__ void operator()(const f32x4 (&acc)[2][2][4][2], const Unit& u, int wr, int wc, int fr, int fq) const {
;         const bf16* const SB = (const bf16*)(ws + WS_SB); bf16* const Y = (bf16*)(ws + WS_H);
;         const int row0 = u.pm * 256 + wr * 64 + fr, col0 = u.pn * 256 + wc * 32 + 8 * fq;
; #pragma unroll
;         for (int ai = 0; ai < 2; ++ai)
; #pragma unroll
;             for (int m = 0; m < 4; ++m) { const size_t off = (size_t)(row0 + ai * 128 + m * 16) * DM + col0;
; #pragma unroll
;                 for (int bj = 0; bj < 2; ++bj) { const v4u g = *(const v4u*)(SB + off + bj * 128); const v4u p = *(const v4u*)(P + off + bj * 128);
;                     const f32x4 a0 = acc[ai][bj][m][0], a1 = acc[ai][bj][m][1];
;                     const f32x4 y0 = {bf_lo(p.x) + a0[0] * bf_lo(g.x), bf_hi(p.x) + a0[1] * bf_hi(g.x), bf_lo(p.y) + a0[2] * bf_lo(g.y), bf_hi(p.y) + a0[3] * bf_hi(g.y)};
;                     const f32x4 y1 = {bf_lo(p.z) + a1[0] * bf_lo(g.z), bf_hi(p.z) + a1[1] * bf_hi(g.z), bf_lo(p.w) + a1[2] * bf_lo(g.w), bf_hi(p.w) + a1[3] * bf_hi(g.w)};
;                     *(v4u*)(Y + off + bj * 128) = pack8(y0, y1); } }
;     }
	v_lshlrev_b32_e32 v42, 16, v224
	v_and_b32_e32 v30, 0xffff0000, v224
	v_lshlrev_b32_e32 v43, 16, v225
	v_and_b32_e32 v31, 0xffff0000, v225
	v_lshlrev_b32_e32 v44, 16, v226
	v_and_b32_e32 v32, 0xffff0000, v226
	v_lshlrev_b32_e32 v45, 16, v227
	v_and_b32_e32 v33, 0xffff0000, v227
	s_waitcnt vmcnt(8)
	v_lshlrev_b32_e32 v46, 16, v228
	v_and_b32_e32 v26, 0xffff0000, v228
	v_lshlrev_b32_e32 v47, 16, v229
	v_and_b32_e32 v27, 0xffff0000, v229
	v_lshlrev_b32_e32 v48, 16, v230
	v_and_b32_e32 v28, 0xffff0000, v230
	v_lshlrev_b32_e32 v49, 16, v231
	v_and_b32_e32 v29, 0xffff0000, v231
	v_fmac_f32_e32 v46, v22, v42
	v_fmac_f32_e32 v26, v23, v30
	v_fmac_f32_e32 v47, v24, v43
	v_fmac_f32_e32 v27, v25, v31
	v_fmac_f32_e32 v48, v18, v44
	v_fmac_f32_e32 v28, v19, v32
	v_fmac_f32_e32 v49, v20, v45
	v_fmac_f32_e32 v29, v21, v33
	v_cvt_pk_bf16_f32 v18, v46, v26
	v_cvt_pk_bf16_f32 v19, v47, v27
	v_cvt_pk_bf16_f32 v20, v48, v28
	v_cvt_pk_bf16_f32 v21, v49, v29
	global_store_dwordx4 v[34:35], v[18:21], off offset:256
	s_nop 0
	s_waitcnt vmcnt(8)
	v_lshlrev_b32_e32 v26, 16, v240
	s_waitcnt vmcnt(7)
	v_lshlrev_b32_e32 v27, 16, v244
	v_and_b32_e32 v18, 0xffff0000, v240
	v_and_b32_e32 v22, 0xffff0000, v244
	v_lshlrev_b32_e32 v28, 16, v241
	v_lshlrev_b32_e32 v29, 16, v245
	v_and_b32_e32 v19, 0xffff0000, v241
	v_and_b32_e32 v23, 0xffff0000, v245
	v_lshlrev_b32_e32 v30, 16, v242
	v_lshlrev_b32_e32 v31, 16, v246
	v_and_b32_e32 v20, 0xffff0000, v242
	v_and_b32_e32 v24, 0xffff0000, v246
	v_fmac_f32_e32 v18, v15, v22
	v_fmac_f32_e32 v19, v17, v23
	v_lshlrev_b32_e32 v32, 16, v243
	v_lshlrev_b32_e32 v33, 16, v247
	v_and_b32_e32 v21, 0xffff0000, v243
	v_and_b32_e32 v25, 0xffff0000, v247
	global_load_dwordx4 v[180:183], v[38:39], off offset:256
	global_load_dwordx4 v[184:187], v[40:41], off offset:256
	v_fmac_f32_e32 v26, v14, v27
	v_fmac_f32_e32 v28, v16, v29
	v_fmac_f32_e32 v30, v10, v31
	v_fmac_f32_e32 v20, v11, v24
	v_cvt_pk_bf16_f32 v10, v26, v18
	v_cvt_pk_bf16_f32 v11, v28, v19
	v_lshl_add_u64 v[18:19], s[36:37], 0, v[36:37]
	v_fmac_f32_e32 v32, v12, v33
	v_fmac_f32_e32 v21, v13, v25
	v_cvt_pk_bf16_f32 v12, v30, v20
	v_cvt_pk_bf16_f32 v13, v32, v21
	global_store_dwordx4 v[18:19], v[10:13], off
	s_waitcnt vmcnt(2)
	v_lshlrev_b32_e32 v20, 16, v180
	v_and_b32_e32 v14, 0xffff0000, v180
	v_lshlrev_b32_e32 v21, 16, v181
	v_and_b32_e32 v15, 0xffff0000, v181
	v_lshlrev_b32_e32 v22, 16, v182
	v_and_b32_e32 v16, 0xffff0000, v182
	v_lshlrev_b32_e32 v23, 16, v183
	v_and_b32_e32 v17, 0xffff0000, v183
	s_waitcnt vmcnt(1)
	v_lshlrev_b32_e32 v24, 16, v184
	v_and_b32_e32 v10, 0xffff0000, v184
	v_lshlrev_b32_e32 v25, 16, v185
	v_and_b32_e32 v11, 0xffff0000, v185
	v_lshlrev_b32_e32 v26, 16, v186
	v_and_b32_e32 v12, 0xffff0000, v186
	v_lshlrev_b32_e32 v27, 16, v187
	v_and_b32_e32 v13, 0xffff0000, v187
	v_fmac_f32_e32 v24, v6, v20
	v_fmac_f32_e32 v10, v7, v14
	v_fmac_f32_e32 v25, v8, v21
	v_fmac_f32_e32 v11, v9, v15
	v_fmac_f32_e32 v26, v2, v22
	v_fmac_f32_e32 v12, v3, v16
	v_fmac_f32_e32 v27, v4, v23
	v_fmac_f32_e32 v13, v5, v17
	v_cvt_pk_bf16_f32 v2, v24, v10
	v_cvt_pk_bf16_f32 v3, v25, v11
	v_cvt_pk_bf16_f32 v4, v26, v12
	v_cvt_pk_bf16_f32 v5, v27, v13
	global_store_dwordx4 v[18:19], v[2:5], off offset:256
	s_cbranch_vccnz .LBB0_1074
	s_andn2_b64 vcc, exec, s[6:7]
	s_cbranch_vccnz .LBB0_1073
	s_barrier
	s_branch .LBB0_1073

; __device__ __forceinline__ v4u pack8(f32x4 a, f32x4 b) { v4u w; w.x = cvt_pk_bf16(a[0], a[1]); w.y = cvt_pk_bf16(a[2], a[3]); w.z = cvt_pk_bf16(b[0], b[1]); w.w = cvt_pk_bf16(b[2], b[3]); return w; }
; __device__ __forceinline__ const float* in_ptr(KA* ka, int i) { asm volatile("" : "+s"(ka)); return ka->in[i]; }
;     __device__ __forceinline__ void operator()(const f32x4 (&acc)[2][2][4][2], const Unit& u, int wr, int wc, int fr, int fq) const {
;         bf16* const X1B = (bf16*)(ws + WS_X1B); float* const ssq2 = (float*)(ws + WS_CTL) + CW_SSQ2;
;         const float* const x = in_ptr(ka, 0);
;         const int col0 = u.pn * 256 + wc * 32 + 8 * fq;
; #pragma unroll
;         for (int ai = 0; ai < 2; ++ai)
; #pragma unroll
;             for (int m = 0; m < 4; ++m) { const int p = ai * 128 + wr * 64 + m * 16 + fr, row = u.pm * 256 + p; float s = 0.f;
;                 const float* xr = x + (size_t)row * DM + col0; bf16* dr = X1B + (size_t)(u.pm * 256 + perm_row(p)) * DM + col0;
; #pragma unroll
;                 for (int bj = 0; bj < 2; ++bj) { const f32x4 v0 = *(const f32x4*)(xr + bj * 128) + acc[ai][bj][m][0], v1 = *(const f32x4*)(xr + bj * 128 + 4) + acc[ai][bj][m][1];
;                     s += (v0[0] * v0[0] + v0[1] * v0[1]) + (v0[2] * v0[2] + v0[3] * v0[3]) + (v1[0] * v1[0] + v1[1] * v1[1]) + (v1[2] * v1[2] + v1[3] * v1[3]);
;                     *(v4u*)(dr + bj * 128) = pack8(v0, v1); }
;                 s += __shfl_xor(s, 16); s += __shfl_xor(s, 32);
;                 if (fq == 0) __hip_atomic_fetch_add(ssq2 + row, s, RLX_AGENT); }
;     }
.LBB0_1206:
	s_mov_b64 s[34:35], s[0:1]
	s_load_dwordx2 s[34:35], s[34:35], 0x0
	s_lshl_b32 s40, s60, 8
	v_lshl_or_b32 v148, s62, 8, v170
	v_add_u32_e32 v150, s40, v152
	v_ashrrev_i32_e32 v149, 31, v148
	v_ashrrev_i32_e32 v151, 31, v150
	s_waitcnt lgkmcnt(0)
	v_lshl_add_u64 v[146:147], v[148:149], 2, s[34:35]
	v_lshlrev_b64 v[176:177], 14, v[150:151]
	v_lshl_add_u64 v[186:187], v[146:147], 0, v[176:177]
	global_load_dwordx4 v[178:181], v[186:187], off
	global_load_dwordx4 v[192:195], v[186:187], off offset:16
	global_load_dwordx4 v[200:203], v[186:187], off offset:512
	global_load_dwordx4 v[204:207], v[186:187], off offset:528
	v_add_u32_e32 v250, s40, v156
	v_ashrrev_i32_e32 v251, 31, v250
	v_lshlrev_b64 v[232:233], 14, v[250:251]
	v_lshl_add_u64 v[252:253], v[146:147], 0, v[232:233]
	global_load_dwordx4 v[208:211], v[252:253], off
	v_add_u32_e32 v250, s40, v156
	v_ashrrev_i32_e32 v251, 31, v250
	v_lshlrev_b64 v[232:233], 14, v[250:251]
	v_lshl_add_u64 v[252:253], v[146:147], 0, v[232:233]
	global_load_dwordx4 v[212:215], v[252:253], off offset:16
	v_add_u32_e32 v250, s40, v156
	v_ashrrev_i32_e32 v251, 31, v250
	v_lshlrev_b64 v[232:233], 14, v[250:251]
	v_lshl_add_u64 v[252:253], v[146:147], 0, v[232:233]
	global_load_dwordx4 v[216:219], v[252:253], off offset:512
	v_add_u32_e32 v250, s40, v156
	v_ashrrev_i32_e32 v251, 31, v250
	v_lshlrev_b64 v[232:233], 14, v[250:251]
	v_lshl_add_u64 v[252:253], v[146:147], 0, v[232:233]
	global_load_dwordx4 v[220:223], v[252:253], off offset:528
	v_add_u32_e32 v250, s40, v158
	v_ashrrev_i32_e32 v251, 31, v250
	v_lshlrev_b64 v[232:233], 14, v[250:251]
	v_lshl_add_u64 v[252:253], v[146:147], 0, v[232:233]
	global_load_dwordx4 v[224:227], v[252:253], off
	v_add_u32_e32 v250, s40, v158
	v_ashrrev_i32_e32 v251, 31, v250
	v_lshlrev_b64 v[232:233], 14, v[250:251]
	v_lshl_add_u64 v[252:253], v[146:147], 0, v[232:233]
	global_load_dwordx4 v[228:231], v[252:253], off offset:16
	v_add_u32_e32 v250, s40, v158
	v_ashrrev_i32_e32 v251, 31, v250
	v_lshlrev_b64 v[232:233], 14, v[250:251]
	v_lshl_add_u64 v[252:253], v[146:147], 0, v[232:233]
	global_load_dwordx4 v[240:243], v[252:253], off offset:512
	v_add_u32_e32 v250, s40, v158
	v_ashrrev_i32_e32 v251, 31, v250
	v_lshlrev_b64 v[232:233], 14, v[250:251]
	v_lshl_add_u64 v[252:253], v[146:147], 0, v[232:233]
	global_load_dwordx4 v[244:247], v[252:253], off offset:528
	v_or_b32_e32 v175, s40, v154
	v_add_u32_e32 v176, s28, v175
	v_or_b32_e32 v188, v176, v155
	v_ashrrev_i32_e32 v189, 31, v188
	v_lshl_add_u64 v[148:149], v[148:149], 1, s[14:15]
	v_lshlrev_b64 v[188:189], 13, v[188:189]
	v_lshl_add_u64 v[188:189], v[148:149], 0, v[188:189]
	s_waitcnt vmcnt(10)
	v_pk_add_f32 v[128:129], v[128:129], v[180:181]
	v_pk_add_f32 v[190:191], v[126:127], v[178:179]
	v_pk_add_f32 v[184:185], v[124:125], v[194:195]
	v_pk_add_f32 v[182:183], v[122:123], v[192:193]
	v_cvt_pk_bf16_f32 v122, v190, v191
	v_cvt_pk_bf16_f32 v123, v128, v129
	v_mul_f32_e32 v177, v191, v191
	v_cvt_pk_bf16_f32 v124, v182, v183
	v_cvt_pk_bf16_f32 v125, v184, v185
	global_store_dwordx4 v[188:189], v[122:125], off
	s_nop 0
	v_mul_f32_e32 v129, v129, v129
	v_and_b32_e32 v123, 64, v174
	v_mul_f32_e32 v183, v183, v183
	v_fmac_f32_e32 v177, v190, v190
	v_fmac_f32_e32 v129, v128, v128
	v_xor_b32_e32 v122, 16, v174
	v_add_u32_e32 v123, 64, v123
	v_mul_f32_e32 v185, v185, v185
	v_fmac_f32_e32 v183, v182, v182
	v_add_f32_e32 v128, v177, v129
	v_cmp_lt_i32_e32 vcc, v122, v123
	v_fmac_f32_e32 v185, v184, v184
	v_add_f32_e32 v128, v128, v183
	v_cndmask_b32_e32 v122, v174, v122, vcc
	v_add_f32_e32 v128, v185, v128
	v_lshlrev_b32_e32 v122, 2, v122
	s_waitcnt vmcnt(10)
	v_pk_add_f32 v[120:121], v[120:121], v[202:203]
	v_pk_add_f32 v[118:119], v[118:119], v[200:201]
	s_waitcnt vmcnt(9)
	v_pk_add_f32 v[126:127], v[114:115], v[204:205]
	v_mul_f32_e32 v114, v119, v119
	v_mul_f32_e32 v115, v121, v121
	v_pk_add_f32 v[124:125], v[116:117], v[206:207]
	v_mul_f32_e32 v116, v127, v127
	v_fmac_f32_e32 v114, v118, v118
	v_fmac_f32_e32 v115, v120, v120
	v_mul_f32_e32 v117, v125, v125
	v_fmac_f32_e32 v116, v126, v126
	v_add_f32_e32 v114, v114, v115
	v_fmac_f32_e32 v117, v124, v124
	v_add_f32_e32 v114, v114, v116
	v_add_f32_e32 v114, v117, v114
	v_add_f32_e32 v114, v128, v114
	ds_bpermute_b32 v115, v122, v114
	v_xor_b32_e32 v116, 32, v174
	v_cmp_lt_i32_e32 vcc, v116, v123
	v_cvt_pk_bf16_f32 v118, v118, v119
	v_cvt_pk_bf16_f32 v119, v120, v121
	s_waitcnt lgkmcnt(0)
	v_add_f32_e32 v114, v114, v115
	v_cvt_pk_bf16_f32 v120, v126, v127
	v_cvt_pk_bf16_f32 v121, v124, v125
	v_cndmask_b32_e32 v116, v174, v116, vcc
	v_lshlrev_b32_e32 v116, 2, v116
	ds_bpermute_b32 v115, v116, v114
	global_store_dwordx4 v[188:189], v[118:121], off offset:256
	s_and_saveexec_b64 s[34:35], s[6:7]
	s_cbranch_execz .LBB0_1208
	v_lshl_add_u64 v[118:119], v[150:151], 2, s[50:51]
	s_waitcnt lgkmcnt(0)
	v_add_f32_e32 v114, v114, v115
	global_atomic_add_f32 v[118:119], v114, off
; __device__ __forceinline__ v4u pack8(f32x4 a, f32x4 b) { v4u w; w.x = cvt_pk_bf16(a[0], a[1]); w.y = cvt_pk_bf16(a[2], a[3]); w.z = cvt_pk_bf16(b[0], b[1]); w.w = cvt_pk_bf16(b[2], b[3]); return w; }
; __device__ __forceinline__ const float* in_ptr(KA* ka, int i) { asm volatile("" : "+s"(ka)); return ka->in[i]; }
;     __device__ __forceinline__ void operator()(const f32x4 (&acc)[2][2][4][2], const Unit& u, int wr, int wc, int fr, int fq) const {
;         bf16* const X1B = (bf16*)(ws + WS_X1B); float* const ssq2 = (float*)(ws + WS_CTL) + CW_SSQ2;
;         const float* const x = in_ptr(ka, 0);
;         const int col0 = u.pn * 256 + wc * 32 + 8 * fq;
; #pragma unroll
;         for (int ai = 0; ai < 2; ++ai)
; #pragma unroll
;             for (int m = 0; m < 4; ++m) { const int p = ai * 128 + wr * 64 + m * 16 + fr, row = u.pm * 256 + p; float s = 0.f;
;                 const float* xr = x + (size_t)row * DM + col0; bf16* dr = X1B + (size_t)(u.pm * 256 + perm_row(p)) * DM + col0;
; #pragma unroll
;                 for (int bj = 0; bj < 2; ++bj) { const f32x4 v0 = *(const f32x4*)(xr + bj * 128) + acc[ai][bj][m][0], v1 = *(const f32x4*)(xr + bj * 128 + 4) + acc[ai][bj][m][1];
;                     s += (v0[0] * v0[0] + v0[1] * v0[1]) + (v0[2] * v0[2] + v0[3] * v0[3]) + (v1[0] * v1[0] + v1[1] * v1[1]) + (v1[2] * v1[2] + v1[3] * v1[3]);
;                     *(v4u*)(dr + bj * 128) = pack8(v0, v1); }
;                 s += __shfl_xor(s, 16); s += __shfl_xor(s, 32);
;                 if (fq == 0) __hip_atomic_fetch_add(ssq2 + row, s, RLX_AGENT); }
;     }
.LBB0_1208:
	s_or_b64 exec, exec, s[34:35]
	v_add_u32_e32 v114, s40, v156
	s_waitcnt lgkmcnt(0)
	v_ashrrev_i32_e32 v115, 31, v114
	v_lshlrev_b64 v[118:119], 14, v[114:115]
	v_lshl_add_u64 v[128:129], v[146:147], 0, v[118:119]
	v_or_b32_e32 v150, v176, v157
	v_ashrrev_i32_e32 v151, 31, v150
	v_lshlrev_b64 v[150:151], 13, v[150:151]
	v_lshl_add_u64 v[150:151], v[148:149], 0, v[150:151]
	s_waitcnt vmcnt(9)
	v_pk_add_f32 v[120:121], v[112:113], v[210:211]
	v_pk_add_f32 v[118:119], v[110:111], v[208:209]
	s_waitcnt vmcnt(8)
	v_pk_add_f32 v[126:127], v[108:109], v[214:215]
	v_pk_add_f32 v[124:125], v[106:107], v[212:213]
	v_cvt_pk_bf16_f32 v106, v118, v119
	v_cvt_pk_bf16_f32 v107, v120, v121
	v_mul_f32_e32 v117, v119, v119
	v_cvt_pk_bf16_f32 v108, v124, v125
	v_cvt_pk_bf16_f32 v109, v126, v127
	global_store_dwordx4 v[150:151], v[106:109], off
	s_nop 0
	v_mul_f32_e32 v119, v121, v121
	v_mul_f32_e32 v121, v125, v125
	v_fmac_f32_e32 v117, v118, v118
	v_fmac_f32_e32 v119, v120, v120
	v_mul_f32_e32 v123, v127, v127
	v_fmac_f32_e32 v121, v124, v124
	v_add_f32_e32 v117, v117, v119
	v_fmac_f32_e32 v123, v126, v126
	v_add_f32_e32 v117, v117, v121
	v_add_f32_e32 v117, v123, v117
	s_waitcnt vmcnt(8)
	v_pk_add_f32 v[104:105], v[104:105], v[218:219]
	v_pk_add_f32 v[102:103], v[102:103], v[216:217]
	s_waitcnt vmcnt(7)
	v_pk_add_f32 v[108:109], v[98:99], v[220:221]
	v_mul_f32_e32 v98, v103, v103
	v_mul_f32_e32 v99, v105, v105
	v_pk_add_f32 v[106:107], v[100:101], v[222:223]
	v_mul_f32_e32 v100, v109, v109
	v_fmac_f32_e32 v98, v102, v102
	v_fmac_f32_e32 v99, v104, v104
	v_mul_f32_e32 v101, v107, v107
	v_fmac_f32_e32 v100, v108, v108
	v_add_f32_e32 v98, v98, v99
	v_add_f32_e32 v98, v98, v100
	v_fmac_f32_e32 v101, v106, v106
	v_add_f32_e32 v98, v101, v98
	v_add_f32_e32 v98, v117, v98
	ds_bpermute_b32 v99, v122, v98
	v_cvt_pk_bf16_f32 v100, v102, v103
	v_cvt_pk_bf16_f32 v101, v104, v105
	v_cvt_pk_bf16_f32 v102, v108, v109
	v_cvt_pk_bf16_f32 v103, v106, v107
	s_waitcnt lgkmcnt(0)
	v_add_f32_e32 v98, v98, v99
	ds_bpermute_b32 v99, v116, v98
	global_store_dwordx4 v[150:151], v[100:103], off offset:256
	s_and_saveexec_b64 s[34:35], s[6:7]
	s_cbranch_execz .LBB0_1210
	v_lshl_add_u64 v[100:101], v[114:115], 2, s[50:51]
	s_waitcnt lgkmcnt(0)
	v_add_f32_e32 v98, v98, v99
	global_atomic_add_f32 v[100:101], v98, off
.LBB0_1210:
	s_or_b64 exec, exec, s[34:35]
	v_add_u32_e32 v98, s40, v158
	s_waitcnt lgkmcnt(0)
	v_ashrrev_i32_e32 v99, 31, v98
	v_lshlrev_b64 v[100:101], 14, v[98:99]
	v_lshl_add_u64 v[108:109], v[146:147], 0, v[100:101]
	v_or_b32_e32 v110, v176, v159
	v_ashrrev_i32_e32 v111, 31, v110
	v_lshlrev_b64 v[110:111], 13, v[110:111]
	v_lshl_add_u64 v[110:111], v[148:149], 0, v[110:111]
	s_waitcnt vmcnt(7)
	v_pk_add_f32 v[102:103], v[96:97], v[226:227]
	v_pk_add_f32 v[100:101], v[94:95], v[224:225]
	s_waitcnt vmcnt(6)
	v_pk_add_f32 v[106:107], v[92:93], v[230:231]
	v_pk_add_f32 v[104:105], v[90:91], v[228:229]
	v_cvt_pk_bf16_f32 v90, v100, v101
	v_cvt_pk_bf16_f32 v91, v102, v103
	v_mul_f32_e32 v101, v101, v101
	v_cvt_pk_bf16_f32 v92, v104, v105
	v_cvt_pk_bf16_f32 v93, v106, v107
	global_store_dwordx4 v[110:111], v[90:93], off
	s_nop 0
	v_mul_f32_e32 v103, v103, v103
	v_mul_f32_e32 v105, v105, v105
	v_fmac_f32_e32 v101, v100, v100
	v_fmac_f32_e32 v103, v102, v102
	v_mul_f32_e32 v107, v107, v107
	v_fmac_f32_e32 v105, v104, v104
	v_add_f32_e32 v100, v101, v103
	v_fmac_f32_e32 v107, v106, v106
	v_add_f32_e32 v100, v100, v105
	v_add_f32_e32 v100, v107, v100
	s_waitcnt vmcnt(6)
	v_pk_add_f32 v[88:89], v[88:89], v[242:243]
	v_pk_add_f32 v[86:87], v[86:87], v[240:241]
	s_waitcnt vmcnt(5)
	v_pk_add_f32 v[92:93], v[82:83], v[244:245]
	v_mul_f32_e32 v82, v87, v87
	v_mul_f32_e32 v83, v89, v89
	v_pk_add_f32 v[90:91], v[84:85], v[246:247]
	v_add_u32_e32 v250, s40, v160
	v_ashrrev_i32_e32 v251, 31, v250
	v_lshlrev_b64 v[232:233], 14, v[250:251]
	v_lshl_add_u64 v[252:253], v[146:147], 0, v[232:233]
	global_load_dwordx4 v[192:195], v[252:253], off
	v_add_u32_e32 v250, s40, v160
	v_ashrrev_i32_e32 v251, 31, v250
	v_lshlrev_b64 v[232:233], 14, v[250:251]
	v_lshl_add_u64 v[252:253], v[146:147], 0, v[232:233]
	global_load_dwordx4 v[200:203], v[252:253], off offset:16
	v_add_u32_e32 v250, s40, v160
	v_ashrrev_i32_e32 v251, 31, v250
	v_lshlrev_b64 v[232:233], 14, v[250:251]
	v_lshl_add_u64 v[252:253], v[146:147], 0, v[232:233]
	global_load_dwordx4 v[204:207], v[252:253], off offset:512
	v_add_u32_e32 v250, s40, v160
	v_ashrrev_i32_e32 v251, 31, v250
	v_lshlrev_b64 v[232:233], 14, v[250:251]
	v_lshl_add_u64 v[252:253], v[146:147], 0, v[232:233]
	global_load_dwordx4 v[208:211], v[252:253], off offset:528
	v_add_u32_e32 v250, s40, v161
	v_ashrrev_i32_e32 v251, 31, v250
	v_lshlrev_b64 v[232:233], 14, v[250:251]
	v_lshl_add_u64 v[252:253], v[146:147], 0, v[232:233]
	global_load_dwordx4 v[212:215], v[252:253], off
	v_add_u32_e32 v250, s40, v161
	v_ashrrev_i32_e32 v251, 31, v250
	v_lshlrev_b64 v[232:233], 14, v[250:251]
	v_lshl_add_u64 v[252:253], v[146:147], 0, v[232:233]
	global_load_dwordx4 v[216:219], v[252:253], off offset:16
	v_add_u32_e32 v250, s40, v161
	v_ashrrev_i32_e32 v251, 31, v250
	v_lshlrev_b64 v[232:233], 14, v[250:251]
	v_lshl_add_u64 v[252:253], v[146:147], 0, v[232:233]
	global_load_dwordx4 v[220:223], v[252:253], off offset:512
	v_add_u32_e32 v250, s40, v161
	v_ashrrev_i32_e32 v251, 31, v250
	v_lshlrev_b64 v[232:233], 14, v[250:251]
	v_lshl_add_u64 v[252:253], v[146:147], 0, v[232:233]
	global_load_dwordx4 v[224:227], v[252:253], off offset:528
	v_add_u32_e32 v250, s40, v163
	v_ashrrev_i32_e32 v251, 31, v250
	v_lshlrev_b64 v[232:233], 14, v[250:251]
	v_lshl_add_u64 v[252:253], v[146:147], 0, v[232:233]
	global_load_dwordx4 v[228:231], v[252:253], off
	v_add_u32_e32 v250, s40, v163
	v_ashrrev_i32_e32 v251, 31, v250
	v_lshlrev_b64 v[232:233], 14, v[250:251]
	v_lshl_add_u64 v[252:253], v[146:147], 0, v[232:233]
	global_load_dwordx4 v[240:243], v[252:253], off offset:16
	v_add_u32_e32 v250, s40, v163
	v_ashrrev_i32_e32 v251, 31, v250
	v_lshlrev_b64 v[232:233], 14, v[250:251]
	v_lshl_add_u64 v[252:253], v[146:147], 0, v[232:233]
	global_load_dwordx4 v[244:247], v[252:253], off offset:512
	v_mul_f32_e32 v84, v93, v93
	v_fmac_f32_e32 v82, v86, v86
	v_fmac_f32_e32 v83, v88, v88
	v_mul_f32_e32 v85, v91, v91
	v_fmac_f32_e32 v84, v92, v92
	v_add_f32_e32 v82, v82, v83
	v_add_f32_e32 v82, v82, v84
	v_fmac_f32_e32 v85, v90, v90
	v_add_f32_e32 v82, v85, v82
	v_add_f32_e32 v82, v100, v82
	ds_bpermute_b32 v83, v122, v82
	v_cvt_pk_bf16_f32 v84, v86, v87
	v_cvt_pk_bf16_f32 v85, v88, v89
	v_cvt_pk_bf16_f32 v86, v92, v93
	v_cvt_pk_bf16_f32 v87, v90, v91
	s_waitcnt lgkmcnt(0)
	v_add_f32_e32 v82, v82, v83
	ds_bpermute_b32 v83, v116, v82
	global_store_dwordx4 v[110:111], v[84:87], off offset:256
	s_mov_b64 s[34:35], exec
	s_and_b64 s[60:61], s[34:35], s[6:7]
	v_and_b32_e32 v248, 63, v0
	s_mov_b64 exec, s[60:61]
	s_cbranch_execz .LBB0_1212
	v_lshl_add_u64 v[84:85], v[98:99], 2, s[50:51]
	s_waitcnt lgkmcnt(0)
	v_add_f32_e32 v82, v82, v83
	global_atomic_add_f32 v[84:85], v82, off
; __device__ __forceinline__ v4u pack8(f32x4 a, f32x4 b) { v4u w; w.x = cvt_pk_bf16(a[0], a[1]); w.y = cvt_pk_bf16(a[2], a[3]); w.z = cvt_pk_bf16(b[0], b[1]); w.w = cvt_pk_bf16(b[2], b[3]); return w; }
; __device__ __forceinline__ const float* in_ptr(KA* ka, int i) { asm volatile("" : "+s"(ka)); return ka->in[i]; }
;     __device__ __forceinline__ void operator()(const f32x4 (&acc)[2][2][4][2], const Unit& u, int wr, int wc, int fr, int fq) const {
;         bf16* const X1B = (bf16*)(ws + WS_X1B); float* const ssq2 = (float*)(ws + WS_CTL) + CW_SSQ2;
;         const float* const x = in_ptr(ka, 0);
;         const int col0 = u.pn * 256 + wc * 32 + 8 * fq;
; #pragma unroll
;         for (int ai = 0; ai < 2; ++ai)
; #pragma unroll
;             for (int m = 0; m < 4; ++m) { const int p = ai * 128 + wr * 64 + m * 16 + fr, row = u.pm * 256 + p; float s = 0.f;
;                 const float* xr = x + (size_t)row * DM + col0; bf16* dr = X1B + (size_t)(u.pm * 256 + perm_row(p)) * DM + col0;
; #pragma unroll
;                 for (int bj = 0; bj < 2; ++bj) { const f32x4 v0 = *(const f32x4*)(xr + bj * 128) + acc[ai][bj][m][0], v1 = *(const f32x4*)(xr + bj * 128 + 4) + acc[ai][bj][m][1];
;                     s += (v0[0] * v0[0] + v0[1] * v0[1]) + (v0[2] * v0[2] + v0[3] * v0[3]) + (v1[0] * v1[0] + v1[1] * v1[1]) + (v1[2] * v1[2] + v1[3] * v1[3]);
;                     *(v4u*)(dr + bj * 128) = pack8(v0, v1); }
;                 s += __shfl_xor(s, 16); s += __shfl_xor(s, 32);
;                 if (fq == 0) __hip_atomic_fetch_add(ssq2 + row, s, RLX_AGENT); }
;     }
.LBB0_1212:
	s_or_b64 exec, exec, s[34:35]
	v_add_u32_e32 v82, s40, v160
	s_waitcnt lgkmcnt(0)
	v_ashrrev_i32_e32 v83, 31, v82
	v_lshlrev_b64 v[84:85], 14, v[82:83]
	v_lshl_add_u64 v[92:93], v[146:147], 0, v[84:85]
	v_bfe_u32 v94, v160, 3, 4
	v_or_b32_e32 v94, v176, v94
	v_ashrrev_i32_e32 v95, 31, v94
	v_lshlrev_b64 v[94:95], 13, v[94:95]
	v_lshl_add_u64 v[94:95], v[148:149], 0, v[94:95]
	s_waitcnt vmcnt(11)
	v_pk_add_f32 v[86:87], v[80:81], v[194:195]
	v_pk_add_f32 v[84:85], v[78:79], v[192:193]
	s_waitcnt vmcnt(10)
	v_pk_add_f32 v[90:91], v[76:77], v[202:203]
	v_pk_add_f32 v[88:89], v[74:75], v[200:201]
	v_cvt_pk_bf16_f32 v74, v84, v85
	v_cvt_pk_bf16_f32 v75, v86, v87
	v_mul_f32_e32 v85, v85, v85
	v_cvt_pk_bf16_f32 v76, v88, v89
	v_cvt_pk_bf16_f32 v77, v90, v91
	global_store_dwordx4 v[94:95], v[74:77], off
	s_nop 0
	v_mul_f32_e32 v87, v87, v87
	v_mul_f32_e32 v89, v89, v89
	v_fmac_f32_e32 v85, v84, v84
	v_fmac_f32_e32 v87, v86, v86
	v_mul_f32_e32 v91, v91, v91
	v_fmac_f32_e32 v89, v88, v88
	v_add_f32_e32 v84, v85, v87
	v_fmac_f32_e32 v91, v90, v90
	v_add_f32_e32 v84, v84, v89
	v_add_f32_e32 v84, v91, v84
	s_waitcnt vmcnt(10)
	v_pk_add_f32 v[72:73], v[72:73], v[206:207]
	v_pk_add_f32 v[70:71], v[70:71], v[204:205]
	s_waitcnt vmcnt(9)
	v_pk_add_f32 v[76:77], v[66:67], v[208:209]
	v_mul_f32_e32 v66, v71, v71
	v_mul_f32_e32 v67, v73, v73
	v_pk_add_f32 v[74:75], v[68:69], v[210:211]
	v_mul_f32_e32 v68, v77, v77
	v_fmac_f32_e32 v66, v70, v70
	v_fmac_f32_e32 v67, v72, v72
	v_mul_f32_e32 v69, v75, v75
	v_fmac_f32_e32 v68, v76, v76
	v_add_f32_e32 v66, v66, v67
	v_add_f32_e32 v66, v66, v68
	v_fmac_f32_e32 v69, v74, v74
	v_add_f32_e32 v66, v69, v66
	v_add_f32_e32 v66, v84, v66
	ds_bpermute_b32 v67, v122, v66
	v_cvt_pk_bf16_f32 v68, v70, v71
	v_cvt_pk_bf16_f32 v69, v72, v73
	v_cvt_pk_bf16_f32 v70, v76, v77
	v_cvt_pk_bf16_f32 v71, v74, v75
	s_waitcnt lgkmcnt(0)
	v_add_f32_e32 v66, v66, v67
	ds_bpermute_b32 v67, v116, v66
	global_store_dwordx4 v[94:95], v[68:71], off offset:256
	s_and_saveexec_b64 s[34:35], s[6:7]
	s_cbranch_execz .LBB0_1214
	v_lshl_add_u64 v[68:69], v[82:83], 2, s[50:51]
	s_waitcnt lgkmcnt(0)
	v_add_f32_e32 v66, v66, v67
	global_atomic_add_f32 v[68:69], v66, off
.LBB0_1214:
	s_or_b64 exec, exec, s[34:35]
	v_add_u32_e32 v66, s40, v161
	s_waitcnt lgkmcnt(0)
	v_ashrrev_i32_e32 v67, 31, v66
	v_lshlrev_b64 v[68:69], 14, v[66:67]
	v_lshl_add_u64 v[78:79], v[146:147], 0, v[68:69]
	v_add_u32_e32 v68, s29, v175
	v_or_b32_e32 v80, v68, v162
	v_ashrrev_i32_e32 v81, 31, v80
	v_lshlrev_b64 v[80:81], 13, v[80:81]
	v_lshl_add_u64 v[80:81], v[148:149], 0, v[80:81]
	s_waitcnt vmcnt(9)
	v_pk_add_f32 v[72:73], v[64:65], v[214:215]
	v_pk_add_f32 v[70:71], v[62:63], v[212:213]
	s_waitcnt vmcnt(8)
	v_pk_add_f32 v[76:77], v[60:61], v[218:219]
	v_pk_add_f32 v[74:75], v[58:59], v[216:217]
	v_cvt_pk_bf16_f32 v58, v70, v71
	v_cvt_pk_bf16_f32 v59, v72, v73
	v_mul_f32_e32 v69, v71, v71
	v_cvt_pk_bf16_f32 v60, v74, v75
	v_cvt_pk_bf16_f32 v61, v76, v77
	global_store_dwordx4 v[80:81], v[58:61], off
	s_nop 0
	v_mul_f32_e32 v71, v73, v73
	v_mul_f32_e32 v73, v75, v75
	v_fmac_f32_e32 v69, v70, v70
	v_fmac_f32_e32 v71, v72, v72
	v_mul_f32_e32 v75, v77, v77
	v_fmac_f32_e32 v73, v74, v74
	v_add_f32_e32 v69, v69, v71
	v_fmac_f32_e32 v75, v76, v76
	v_add_f32_e32 v69, v69, v73
	v_add_f32_e32 v69, v75, v69
	s_waitcnt vmcnt(8)
	v_pk_add_f32 v[56:57], v[56:57], v[222:223]
	v_pk_add_f32 v[54:55], v[54:55], v[220:221]
	s_waitcnt vmcnt(7)
	v_pk_add_f32 v[60:61], v[50:51], v[224:225]
	v_mul_f32_e32 v50, v55, v55
	v_mul_f32_e32 v51, v57, v57
	v_pk_add_f32 v[58:59], v[52:53], v[226:227]
	v_mul_f32_e32 v52, v61, v61
	v_fmac_f32_e32 v50, v54, v54
	v_fmac_f32_e32 v51, v56, v56
	v_mul_f32_e32 v53, v59, v59
	v_fmac_f32_e32 v52, v60, v60
	v_add_f32_e32 v50, v50, v51
	v_add_f32_e32 v50, v50, v52
	v_fmac_f32_e32 v53, v58, v58
	v_add_f32_e32 v50, v53, v50
	v_add_f32_e32 v50, v69, v50
	ds_bpermute_b32 v51, v122, v50
	v_cvt_pk_bf16_f32 v52, v54, v55
	v_cvt_pk_bf16_f32 v53, v56, v57
	v_cvt_pk_bf16_f32 v54, v60, v61
	v_cvt_pk_bf16_f32 v55, v58, v59
	s_waitcnt lgkmcnt(0)
	v_add_f32_e32 v50, v50, v51
	ds_bpermute_b32 v51, v116, v50
	global_store_dwordx4 v[80:81], v[52:55], off offset:256
	s_and_saveexec_b64 s[34:35], s[6:7]
	s_cbranch_execz .LBB0_1216
	v_lshl_add_u64 v[52:53], v[66:67], 2, s[50:51]
	s_waitcnt lgkmcnt(0)
	v_add_f32_e32 v50, v50, v51
	global_atomic_add_f32 v[52:53], v50, off
; __device__ __forceinline__ v4u pack8(f32x4 a, f32x4 b) { v4u w; w.x = cvt_pk_bf16(a[0], a[1]); w.y = cvt_pk_bf16(a[2], a[3]); w.z = cvt_pk_bf16(b[0], b[1]); w.w = cvt_pk_bf16(b[2], b[3]); return w; }
; __device__ __forceinline__ const float* in_ptr(KA* ka, int i) { asm volatile("" : "+s"(ka)); return ka->in[i]; }
;     __device__ __forceinline__ void operator()(const f32x4 (&acc)[2][2][4][2], const Unit& u, int wr, int wc, int fr, int fq) const {
;         bf16* const X1B = (bf16*)(ws + WS_X1B); float* const ssq2 = (float*)(ws + WS_CTL) + CW_SSQ2;
;         const float* const x = in_ptr(ka, 0);
;         const int col0 = u.pn * 256 + wc * 32 + 8 * fq;
; #pragma unroll
;         for (int ai = 0; ai < 2; ++ai)
; #pragma unroll
;             for (int m = 0; m < 4; ++m) { const int p = ai * 128 + wr * 64 + m * 16 + fr, row = u.pm * 256 + p; float s = 0.f;
;                 const float* xr = x + (size_t)row * DM + col0; bf16* dr = X1B + (size_t)(u.pm * 256 + perm_row(p)) * DM + col0;
; #pragma unroll
;                 for (int bj = 0; bj < 2; ++bj) { const f32x4 v0 = *(const f32x4*)(xr + bj * 128) + acc[ai][bj][m][0], v1 = *(const f32x4*)(xr + bj * 128 + 4) + acc[ai][bj][m][1];
;                     s += (v0[0] * v0[0] + v0[1] * v0[1]) + (v0[2] * v0[2] + v0[3] * v0[3]) + (v1[0] * v1[0] + v1[1] * v1[1]) + (v1[2] * v1[2] + v1[3] * v1[3]);
;                     *(v4u*)(dr + bj * 128) = pack8(v0, v1); }
;                 s += __shfl_xor(s, 16); s += __shfl_xor(s, 32);
;                 if (fq == 0) __hip_atomic_fetch_add(ssq2 + row, s, RLX_AGENT); }
;     }
.LBB0_1216:
	s_or_b64 exec, exec, s[34:35]
	v_add_u32_e32 v50, s40, v163
	s_waitcnt lgkmcnt(0)
	v_ashrrev_i32_e32 v51, 31, v50
	v_lshlrev_b64 v[52:53], 14, v[50:51]
	v_lshl_add_u64 v[60:61], v[146:147], 0, v[52:53]
	v_or_b32_e32 v62, v68, v165
	v_ashrrev_i32_e32 v63, 31, v62
	v_lshlrev_b64 v[62:63], 13, v[62:63]
	v_lshl_add_u64 v[62:63], v[148:149], 0, v[62:63]
	s_waitcnt vmcnt(7)
	v_pk_add_f32 v[54:55], v[48:49], v[230:231]
	v_pk_add_f32 v[52:53], v[46:47], v[228:229]
	s_waitcnt vmcnt(6)
	v_pk_add_f32 v[58:59], v[44:45], v[242:243]
	v_pk_add_f32 v[56:57], v[42:43], v[240:241]
	v_cvt_pk_bf16_f32 v42, v52, v53
	v_cvt_pk_bf16_f32 v43, v54, v55
	v_mul_f32_e32 v53, v53, v53
	v_cvt_pk_bf16_f32 v44, v56, v57
	v_cvt_pk_bf16_f32 v45, v58, v59
	global_store_dwordx4 v[62:63], v[42:45], off
	s_nop 0
	global_load_dwordx4 v[46:49], v[60:61], off offset:528
	v_mul_f32_e32 v55, v55, v55
	v_mul_f32_e32 v57, v57, v57
	v_fmac_f32_e32 v53, v52, v52
	v_fmac_f32_e32 v55, v54, v54
	v_mul_f32_e32 v59, v59, v59
	v_fmac_f32_e32 v57, v56, v56
	v_add_f32_e32 v52, v53, v55
	v_fmac_f32_e32 v59, v58, v58
	v_add_f32_e32 v52, v52, v57
	v_add_f32_e32 v52, v59, v52
	s_waitcnt vmcnt(7)
	v_pk_add_f32 v[40:41], v[40:41], v[246:247]
	v_pk_add_f32 v[38:39], v[38:39], v[244:245]
	v_add_u32_e32 v250, s40, v166
	v_ashrrev_i32_e32 v251, 31, v250
	v_lshlrev_b64 v[232:233], 14, v[250:251]
	v_lshl_add_u64 v[252:253], v[146:147], 0, v[232:233]
	global_load_dwordx4 v[192:195], v[252:253], off
	v_add_u32_e32 v250, s40, v166
	v_ashrrev_i32_e32 v251, 31, v250
	v_lshlrev_b64 v[232:233], 14, v[250:251]
	v_lshl_add_u64 v[252:253], v[146:147], 0, v[232:233]
	global_load_dwordx4 v[200:203], v[252:253], off offset:16
	v_add_u32_e32 v250, s40, v166
	v_ashrrev_i32_e32 v251, 31, v250
	v_lshlrev_b64 v[232:233], 14, v[250:251]
	v_lshl_add_u64 v[252:253], v[146:147], 0, v[232:233]
	global_load_dwordx4 v[204:207], v[252:253], off offset:512
	v_add_u32_e32 v250, s40, v166
	v_ashrrev_i32_e32 v251, 31, v250
	v_lshlrev_b64 v[232:233], 14, v[250:251]
	v_lshl_add_u64 v[252:253], v[146:147], 0, v[232:233]
	global_load_dwordx4 v[208:211], v[252:253], off offset:528
	v_add_u32_e32 v250, s40, v169
	v_ashrrev_i32_e32 v251, 31, v250
	v_lshlrev_b64 v[232:233], 14, v[250:251]
	v_lshl_add_u64 v[252:253], v[146:147], 0, v[232:233]
	global_load_dwordx4 v[212:215], v[252:253], off
	v_add_u32_e32 v250, s40, v169
	v_ashrrev_i32_e32 v251, 31, v250
	v_lshlrev_b64 v[232:233], 14, v[250:251]
	v_lshl_add_u64 v[252:253], v[146:147], 0, v[232:233]
	global_load_dwordx4 v[216:219], v[252:253], off offset:16
	v_add_u32_e32 v250, s40, v169
	v_ashrrev_i32_e32 v251, 31, v250
	v_lshlrev_b64 v[232:233], 14, v[250:251]
	v_lshl_add_u64 v[252:253], v[146:147], 0, v[232:233]
	global_load_dwordx4 v[220:223], v[252:253], off offset:512
	v_add_u32_e32 v250, s40, v169
	v_ashrrev_i32_e32 v251, 31, v250
	v_lshlrev_b64 v[232:233], 14, v[250:251]
	v_lshl_add_u64 v[252:253], v[146:147], 0, v[232:233]
	global_load_dwordx4 v[224:227], v[252:253], off offset:528
	s_waitcnt vmcnt(8)
	v_pk_add_f32 v[44:45], v[34:35], v[46:47]
	v_mul_f32_e32 v34, v39, v39
	v_mul_f32_e32 v35, v41, v41
	v_pk_add_f32 v[42:43], v[36:37], v[48:49]
	v_mul_f32_e32 v36, v45, v45
	v_fmac_f32_e32 v34, v38, v38
	v_fmac_f32_e32 v35, v40, v40
	v_mul_f32_e32 v37, v43, v43
	v_fmac_f32_e32 v36, v44, v44
	v_add_f32_e32 v34, v34, v35
	v_add_f32_e32 v34, v34, v36
	v_fmac_f32_e32 v37, v42, v42
	v_add_f32_e32 v34, v37, v34
	v_add_f32_e32 v34, v52, v34
	ds_bpermute_b32 v35, v122, v34
	v_cvt_pk_bf16_f32 v36, v38, v39
	v_cvt_pk_bf16_f32 v37, v40, v41
	v_cvt_pk_bf16_f32 v38, v44, v45
	v_cvt_pk_bf16_f32 v39, v42, v43
	s_waitcnt lgkmcnt(0)
	v_add_f32_e32 v34, v34, v35
	ds_bpermute_b32 v35, v116, v34
	global_store_dwordx4 v[62:63], v[36:39], off offset:256
	s_and_saveexec_b64 s[34:35], s[6:7]
	s_cbranch_execz .LBB0_1218
	v_lshl_add_u64 v[36:37], v[50:51], 2, s[50:51]
	s_waitcnt lgkmcnt(0)
	v_add_f32_e32 v34, v34, v35
	global_atomic_add_f32 v[36:37], v34, off
; __device__ __forceinline__ v4u pack8(f32x4 a, f32x4 b) { v4u w; w.x = cvt_pk_bf16(a[0], a[1]); w.y = cvt_pk_bf16(a[2], a[3]); w.z = cvt_pk_bf16(b[0], b[1]); w.w = cvt_pk_bf16(b[2], b[3]); return w; }
; __device__ __forceinline__ const float* in_ptr(KA* ka, int i) { asm volatile("" : "+s"(ka)); return ka->in[i]; }
;     __device__ __forceinline__ void operator()(const f32x4 (&acc)[2][2][4][2], const Unit& u, int wr, int wc, int fr, int fq) const {
;         bf16* const X1B = (bf16*)(ws + WS_X1B); float* const ssq2 = (float*)(ws + WS_CTL) + CW_SSQ2;
;         const float* const x = in_ptr(ka, 0);
;         const int col0 = u.pn * 256 + wc * 32 + 8 * fq;
; #pragma unroll
;         for (int ai = 0; ai < 2; ++ai)
; #pragma unroll
;             for (int m = 0; m < 4; ++m) { const int p = ai * 128 + wr * 64 + m * 16 + fr, row = u.pm * 256 + p; float s = 0.f;
;                 const float* xr = x + (size_t)row * DM + col0; bf16* dr = X1B + (size_t)(u.pm * 256 + perm_row(p)) * DM + col0;
; #pragma unroll
;                 for (int bj = 0; bj < 2; ++bj) { const f32x4 v0 = *(const f32x4*)(xr + bj * 128) + acc[ai][bj][m][0], v1 = *(const f32x4*)(xr + bj * 128 + 4) + acc[ai][bj][m][1];
;                     s += (v0[0] * v0[0] + v0[1] * v0[1]) + (v0[2] * v0[2] + v0[3] * v0[3]) + (v1[0] * v1[0] + v1[1] * v1[1]) + (v1[2] * v1[2] + v1[3] * v1[3]);
;                     *(v4u*)(dr + bj * 128) = pack8(v0, v1); }
;                 s += __shfl_xor(s, 16); s += __shfl_xor(s, 32);
;                 if (fq == 0) __hip_atomic_fetch_add(ssq2 + row, s, RLX_AGENT); }
;     }
.LBB0_1218:
	s_or_b64 exec, exec, s[34:35]
	v_add_u32_e32 v34, s40, v166
	s_waitcnt lgkmcnt(0)
	v_ashrrev_i32_e32 v35, 31, v34
	v_lshlrev_b64 v[36:37], 14, v[34:35]
	v_lshl_add_u64 v[44:45], v[146:147], 0, v[36:37]
	v_or_b32_e32 v46, v68, v168
	v_ashrrev_i32_e32 v47, 31, v46
	v_lshlrev_b64 v[46:47], 13, v[46:47]
	v_lshl_add_u64 v[46:47], v[148:149], 0, v[46:47]
	s_waitcnt vmcnt(8)
	v_pk_add_f32 v[38:39], v[32:33], v[194:195]
	v_pk_add_f32 v[36:37], v[30:31], v[192:193]
	s_waitcnt vmcnt(7)
	v_pk_add_f32 v[42:43], v[28:29], v[202:203]
	v_pk_add_f32 v[40:41], v[26:27], v[200:201]
	v_cvt_pk_bf16_f32 v26, v36, v37
	v_cvt_pk_bf16_f32 v27, v38, v39
	v_mul_f32_e32 v37, v37, v37
	v_cvt_pk_bf16_f32 v28, v40, v41
	v_cvt_pk_bf16_f32 v29, v42, v43
	global_store_dwordx4 v[46:47], v[26:29], off
	s_nop 0
	v_mul_f32_e32 v39, v39, v39
	v_mul_f32_e32 v41, v41, v41
	v_fmac_f32_e32 v37, v36, v36
	v_fmac_f32_e32 v39, v38, v38
	v_mul_f32_e32 v43, v43, v43
	v_fmac_f32_e32 v41, v40, v40
	v_add_f32_e32 v36, v37, v39
	v_fmac_f32_e32 v43, v42, v42
	v_add_f32_e32 v36, v36, v41
	v_add_f32_e32 v36, v43, v36
	s_waitcnt vmcnt(7)
	v_pk_add_f32 v[24:25], v[24:25], v[206:207]
	v_pk_add_f32 v[22:23], v[22:23], v[204:205]
	s_waitcnt vmcnt(6)
	v_pk_add_f32 v[28:29], v[18:19], v[208:209]
	v_mul_f32_e32 v18, v23, v23
	v_mul_f32_e32 v19, v25, v25
	v_pk_add_f32 v[26:27], v[20:21], v[210:211]
	v_mul_f32_e32 v20, v29, v29
	v_fmac_f32_e32 v18, v22, v22
	v_fmac_f32_e32 v19, v24, v24
	v_mul_f32_e32 v21, v27, v27
	v_fmac_f32_e32 v20, v28, v28
	v_add_f32_e32 v18, v18, v19
	v_add_f32_e32 v18, v18, v20
	v_fmac_f32_e32 v21, v26, v26
	v_add_f32_e32 v18, v21, v18
	v_add_f32_e32 v18, v36, v18
	ds_bpermute_b32 v19, v122, v18
	v_cvt_pk_bf16_f32 v20, v22, v23
	v_cvt_pk_bf16_f32 v21, v24, v25
	v_cvt_pk_bf16_f32 v22, v28, v29
	v_cvt_pk_bf16_f32 v23, v26, v27
	s_waitcnt lgkmcnt(0)
	v_add_f32_e32 v18, v18, v19
	ds_bpermute_b32 v19, v116, v18
	global_store_dwordx4 v[46:47], v[20:23], off offset:256
	s_and_saveexec_b64 s[34:35], s[6:7]
	s_cbranch_execz .LBB0_1220
	v_lshl_add_u64 v[20:21], v[34:35], 2, s[50:51]
	s_waitcnt lgkmcnt(0)
	v_add_f32_e32 v18, v18, v19
	global_atomic_add_f32 v[20:21], v18, off
.LBB0_1220:
	s_or_b64 exec, exec, s[34:35]
	v_add_u32_e32 v18, s40, v169
	s_waitcnt lgkmcnt(0)
	v_ashrrev_i32_e32 v19, 31, v18
	v_lshlrev_b64 v[20:21], 14, v[18:19]
	v_lshl_add_u64 v[28:29], v[146:147], 0, v[20:21]
	v_bfe_u32 v30, v169, 3, 4
	v_or_b32_e32 v30, v68, v30
	v_ashrrev_i32_e32 v31, 31, v30
	v_lshlrev_b64 v[30:31], 13, v[30:31]
	v_lshl_add_u64 v[30:31], v[148:149], 0, v[30:31]
	s_waitcnt vmcnt(6)
	v_pk_add_f32 v[22:23], v[16:17], v[214:215]
	v_pk_add_f32 v[20:21], v[14:15], v[212:213]
	s_waitcnt vmcnt(5)
	v_pk_add_f32 v[26:27], v[12:13], v[218:219]
	v_pk_add_f32 v[24:25], v[10:11], v[216:217]
	v_cvt_pk_bf16_f32 v10, v20, v21
	v_cvt_pk_bf16_f32 v11, v22, v23
	v_mul_f32_e32 v21, v21, v21
	v_cvt_pk_bf16_f32 v12, v24, v25
	v_cvt_pk_bf16_f32 v13, v26, v27
	global_store_dwordx4 v[30:31], v[10:13], off
	s_nop 0
	v_mul_f32_e32 v23, v23, v23
	v_mul_f32_e32 v25, v25, v25
	v_fmac_f32_e32 v21, v20, v20
	v_fmac_f32_e32 v23, v22, v22
	v_mul_f32_e32 v27, v27, v27
	v_fmac_f32_e32 v25, v24, v24
	v_add_f32_e32 v20, v21, v23
	v_fmac_f32_e32 v27, v26, v26
	v_add_f32_e32 v20, v20, v25
	v_add_f32_e32 v20, v27, v20
	s_waitcnt vmcnt(5)
	v_pk_add_f32 v[8:9], v[8:9], v[222:223]
	v_pk_add_f32 v[6:7], v[6:7], v[220:221]
	s_waitcnt vmcnt(4)
	v_pk_add_f32 v[12:13], v[2:3], v[224:225]
	v_mul_f32_e32 v2, v7, v7
	v_mul_f32_e32 v3, v9, v9
	v_pk_add_f32 v[10:11], v[4:5], v[226:227]
	v_mul_f32_e32 v4, v13, v13
	v_fmac_f32_e32 v2, v6, v6
	v_fmac_f32_e32 v3, v8, v8
	v_mul_f32_e32 v5, v11, v11
	v_fmac_f32_e32 v4, v12, v12
	v_add_f32_e32 v2, v2, v3
	v_add_f32_e32 v2, v2, v4
	v_fmac_f32_e32 v5, v10, v10
	v_add_f32_e32 v2, v5, v2
	v_add_f32_e32 v2, v20, v2
	ds_bpermute_b32 v3, v122, v2
	v_cvt_pk_bf16_f32 v4, v6, v7
	v_cvt_pk_bf16_f32 v5, v8, v9
	v_cvt_pk_bf16_f32 v6, v12, v13
	v_cvt_pk_bf16_f32 v7, v10, v11
	s_waitcnt lgkmcnt(0)
	v_add_f32_e32 v2, v2, v3
	ds_bpermute_b32 v3, v116, v2
	global_store_dwordx4 v[30:31], v[4:7], off offset:256
	s_and_saveexec_b64 s[34:35], s[6:7]
	s_cbranch_execz .LBB0_1222
	v_lshl_add_u64 v[4:5], v[18:19], 2, s[50:51]
	s_waitcnt lgkmcnt(0)
	v_add_f32_e32 v2, v2, v3
	global_atomic_add_f32 v[4:5], v2, off

; __device__ __forceinline__ float bf_lo(unsigned w) { return __uint_as_float(w << 16); }
; __device__ __forceinline__ float bf_hi(unsigned w) { return __uint_as_float(w & 0xffff0000u); }
; __device__ __forceinline__ v4u pack8(f32x4 a, f32x4 b) { v4u w; w.x = cvt_pk_bf16(a[0], a[1]); w.y = cvt_pk_bf16(a[2], a[3]); w.z = cvt_pk_bf16(b[0], b[1]); w.w = cvt_pk_bf16(b[2], b[3]); return w; }
;     __device__ __forceinline__ void operator()(const f32x4 (&acc)[2][2][4][2], const Unit& u, int wr, int wc, int fr, int fq) const {
;         const bf16* const X1B = (const bf16*)(ws + WS_X1B); bf16* const X2B = (bf16*)(ws + WS_X2B);
;         const int col0 = u.pn * 256 + wc * 32 + 8 * fq;
; #pragma unroll
;         for (int ai = 0; ai < 2; ++ai)
; #pragma unroll
;             for (int m = 0; m < 4; ++m) { const int p = ai * 128 + wr * 64 + m * 16 + fr;
;                 const bf16* sr = X1B + (size_t)(u.pm * 256 + perm_row(p)) * DM + col0; bf16* dr = X2B + (size_t)(u.pm * 256 + p) * DM + col0;
; #pragma unroll
;                 for (int bj = 0; bj < 2; ++bj) { const v4u x = *(const v4u*)(sr + bj * 128); const f32x4 a0 = acc[ai][bj][m][0], a1 = acc[ai][bj][m][1];
;                     const f32x4 v0 = {bf_lo(x.x) + a0[0], bf_hi(x.x) + a0[1], bf_lo(x.y) + a0[2], bf_hi(x.y) + a0[3]};
;                     const f32x4 v1 = {bf_lo(x.z) + a1[0], bf_hi(x.z) + a1[1], bf_lo(x.w) + a1[2], bf_hi(x.w) + a1[3]};
;                     *(v4u*)(dr + bj * 128) = pack8(v0, v1); } }
;     }
.LBB0_1734:
	s_lshl_b32 s40, s46, 8
	v_or_b32_e32 v169, s40, v149
	v_lshl_or_b32 v146, s47, 8, v165
	v_add_u32_e32 v178, s30, v169
	v_ashrrev_i32_e32 v147, 31, v146
	v_or_b32_e32 v170, v178, v150
	v_lshlrev_b64 v[174:175], 1, v[146:147]
	v_ashrrev_i32_e32 v171, 31, v170
	v_lshl_add_u64 v[146:147], s[14:15], 0, v[174:175]
	v_lshlrev_b64 v[170:171], 13, v[170:171]
	v_lshl_add_u64 v[176:177], v[146:147], 0, v[170:171]
	global_load_dwordx4 v[170:173], v[176:177], off
	global_load_dwordx4 v[184:187], v[176:177], off offset:256
	v_or_b32_e32 v246, v178, v152
	v_ashrrev_i32_e32 v247, 31, v246
	v_lshlrev_b64 v[246:247], 13, v[246:247]
	v_lshl_add_u64 v[246:247], v[146:147], 0, v[246:247]
	global_load_dwordx4 v[188:191], v[246:247], off
	v_or_b32_e32 v246, v178, v152
	v_ashrrev_i32_e32 v247, 31, v246
	v_lshlrev_b64 v[246:247], 13, v[246:247]
	v_lshl_add_u64 v[246:247], v[146:147], 0, v[246:247]
	global_load_dwordx4 v[192:195], v[246:247], off offset:256
	v_or_b32_e32 v246, v178, v154
	v_ashrrev_i32_e32 v247, 31, v246
	v_lshlrev_b64 v[246:247], 13, v[246:247]
	v_lshl_add_u64 v[246:247], v[146:147], 0, v[246:247]
	global_load_dwordx4 v[196:199], v[246:247], off
	v_or_b32_e32 v246, v178, v154
	v_ashrrev_i32_e32 v247, 31, v246
	v_lshlrev_b64 v[246:247], 13, v[246:247]
	v_lshl_add_u64 v[246:247], v[146:147], 0, v[246:247]
	global_load_dwordx4 v[202:205], v[246:247], off offset:256
	v_or_b32_e32 v246, v178, v156
	v_ashrrev_i32_e32 v247, 31, v246
	v_lshlrev_b64 v[246:247], 13, v[246:247]
	v_lshl_add_u64 v[246:247], v[146:147], 0, v[246:247]
	global_load_dwordx4 v[206:209], v[246:247], off
	v_or_b32_e32 v246, v178, v156
	v_ashrrev_i32_e32 v247, 31, v246
	v_lshlrev_b64 v[246:247], 13, v[246:247]
	v_lshl_add_u64 v[246:247], v[146:147], 0, v[246:247]
	global_load_dwordx4 v[210:213], v[246:247], off offset:256
	v_add_u32_e32 v183, s33, v169
	v_or_b32_e32 v246, v183, v158
	v_ashrrev_i32_e32 v247, 31, v246
	v_lshlrev_b64 v[246:247], 13, v[246:247]
	v_lshl_add_u64 v[246:247], v[146:147], 0, v[246:247]
	global_load_dwordx4 v[214:217], v[246:247], off
	v_add_u32_e32 v183, s33, v169
	v_or_b32_e32 v246, v183, v158
	v_ashrrev_i32_e32 v247, 31, v246
	v_lshlrev_b64 v[246:247], 13, v[246:247]
	v_lshl_add_u64 v[246:247], v[146:147], 0, v[246:247]
	global_load_dwordx4 v[218:221], v[246:247], off offset:256
	v_add_u32_e32 v183, s33, v169
	v_or_b32_e32 v246, v183, v160
	v_ashrrev_i32_e32 v247, 31, v246
	v_lshlrev_b64 v[246:247], 13, v[246:247]
	v_lshl_add_u64 v[246:247], v[146:147], 0, v[246:247]
	global_load_dwordx4 v[222:225], v[246:247], off
	v_add_u32_e32 v183, s33, v169
	v_or_b32_e32 v246, v183, v160
	v_ashrrev_i32_e32 v247, 31, v246
	v_lshlrev_b64 v[246:247], 13, v[246:247]
	v_lshl_add_u64 v[246:247], v[146:147], 0, v[246:247]
	global_load_dwordx4 v[226:229], v[246:247], off offset:256
	v_add_u32_e32 v183, s33, v169
	v_or_b32_e32 v246, v183, v162
	v_ashrrev_i32_e32 v247, 31, v246
	v_lshlrev_b64 v[246:247], 13, v[246:247]
	v_lshl_add_u64 v[246:247], v[146:147], 0, v[246:247]
	global_load_dwordx4 v[230:233], v[246:247], off
	v_add_u32_e32 v183, s33, v169
	v_or_b32_e32 v246, v183, v162
	v_ashrrev_i32_e32 v247, 31, v246
	v_lshlrev_b64 v[246:247], 13, v[246:247]
	v_lshl_add_u64 v[246:247], v[146:147], 0, v[246:247]
	global_load_dwordx4 v[234:237], v[246:247], off offset:256
	v_add_u32_e32 v183, s33, v169
	v_or_b32_e32 v246, v183, v164
	v_ashrrev_i32_e32 v247, 31, v246
	v_lshlrev_b64 v[246:247], 13, v[246:247]
	v_lshl_add_u64 v[246:247], v[146:147], 0, v[246:247]
	global_load_dwordx4 v[238:241], v[246:247], off
	v_add_u32_e32 v183, s33, v169
	v_or_b32_e32 v246, v183, v164
	v_ashrrev_i32_e32 v247, 31, v246
	v_lshlrev_b64 v[246:247], 13, v[246:247]
	v_lshl_add_u64 v[246:247], v[146:147], 0, v[246:247]
	global_load_dwordx4 v[242:245], v[246:247], off offset:256
	s_and_b64 vcc, exec, s[4:5]
	s_mov_b64 s[4:5], -1
	s_waitcnt vmcnt(15)
	v_lshlrev_b32_e32 v179, 16, v170
	v_and_b32_e32 v170, 0xffff0000, v170
	v_lshlrev_b32_e32 v180, 16, v171
	v_and_b32_e32 v171, 0xffff0000, v171
	v_lshlrev_b32_e32 v182, 16, v173
	v_and_b32_e32 v173, 0xffff0000, v173
	v_lshlrev_b32_e32 v181, 16, v172
	v_and_b32_e32 v172, 0xffff0000, v172
	v_add_f32_e32 v126, v126, v179
	v_add_f32_e32 v127, v127, v170
	v_add_f32_e32 v129, v129, v171
	v_add_f32_e32 v170, v124, v182
	v_add_f32_e32 v171, v125, v173
	v_add_f32_e32 v128, v128, v180
	v_add_f32_e32 v122, v122, v181
	v_add_f32_e32 v123, v123, v172
	v_cvt_pk_bf16_f32 v124, v126, v127
	v_cvt_pk_bf16_f32 v125, v128, v129
	v_cvt_pk_bf16_f32 v126, v122, v123
	v_cvt_pk_bf16_f32 v127, v170, v171
	v_add_u32_e32 v128, s40, v1
	v_ashrrev_i32_e32 v129, 31, v128
	v_lshl_add_u64 v[122:123], s[36:37], 0, v[174:175]
	v_lshlrev_b64 v[128:129], 13, v[128:129]
	v_or_b32_e32 v174, v178, v152
	v_lshl_add_u64 v[128:129], v[122:123], 0, v[128:129]
	v_ashrrev_i32_e32 v175, 31, v174
	v_lshlrev_b64 v[174:175], 13, v[174:175]
	global_store_dwordx4 v[128:129], v[124:127], off
	v_lshl_add_u64 v[174:175], v[146:147], 0, v[174:175]
	s_waitcnt vmcnt(15)
	v_lshlrev_b32_e32 v124, 16, v184
	v_and_b32_e32 v125, 0xffff0000, v184
	v_lshlrev_b32_e32 v126, 16, v185
	v_and_b32_e32 v127, 0xffff0000, v185
	v_lshlrev_b32_e32 v170, 16, v186
	v_and_b32_e32 v171, 0xffff0000, v186
	v_lshlrev_b32_e32 v172, 16, v187
	v_and_b32_e32 v173, 0xffff0000, v187
	v_add_f32_e32 v118, v118, v124
	v_add_f32_e32 v119, v119, v125
	v_add_f32_e32 v120, v120, v126
	v_add_f32_e32 v121, v121, v127
	v_add_f32_e32 v117, v117, v173
	v_add_f32_e32 v124, v114, v170
	v_add_f32_e32 v125, v115, v171
	v_add_f32_e32 v126, v116, v172
	v_cvt_pk_bf16_f32 v114, v118, v119
	v_cvt_pk_bf16_f32 v115, v120, v121
	v_cvt_pk_bf16_f32 v116, v124, v125
	v_cvt_pk_bf16_f32 v117, v126, v117
	s_nop 0
	global_store_dwordx4 v[128:129], v[114:117], off offset:256
	s_waitcnt vmcnt(15)
; __device__ __forceinline__ float bf_lo(unsigned w) { return __uint_as_float(w << 16); }
; __device__ __forceinline__ float bf_hi(unsigned w) { return __uint_as_float(w & 0xffff0000u); }
; __device__ __forceinline__ v4u pack8(f32x4 a, f32x4 b) { v4u w; w.x = cvt_pk_bf16(a[0], a[1]); w.y = cvt_pk_bf16(a[2], a[3]); w.z = cvt_pk_bf16(b[0], b[1]); w.w = cvt_pk_bf16(b[2], b[3]); return w; }
;     __device__ __forceinline__ void operator()(const f32x4 (&acc)[2][2][4][2], const Unit& u, int wr, int wc, int fr, int fq) const {
;         const bf16* const X1B = (const bf16*)(ws + WS_X1B); bf16* const X2B = (bf16*)(ws + WS_X2B);
;         const int col0 = u.pn * 256 + wc * 32 + 8 * fq;
; #pragma unroll
;         for (int ai = 0; ai < 2; ++ai)
; #pragma unroll
;             for (int m = 0; m < 4; ++m) { const int p = ai * 128 + wr * 64 + m * 16 + fr;
;                 const bf16* sr = X1B + (size_t)(u.pm * 256 + perm_row(p)) * DM + col0; bf16* dr = X2B + (size_t)(u.pm * 256 + p) * DM + col0;
; #pragma unroll
;                 for (int bj = 0; bj < 2; ++bj) { const v4u x = *(const v4u*)(sr + bj * 128); const f32x4 a0 = acc[ai][bj][m][0], a1 = acc[ai][bj][m][1];
;                     const f32x4 v0 = {bf_lo(x.x) + a0[0], bf_hi(x.x) + a0[1], bf_lo(x.y) + a0[2], bf_hi(x.y) + a0[3]};
;                     const f32x4 v1 = {bf_lo(x.z) + a1[0], bf_hi(x.z) + a1[1], bf_lo(x.w) + a1[2], bf_hi(x.w) + a1[3]};
;                     *(v4u*)(dr + bj * 128) = pack8(v0, v1); } }
;     }
	s_nop 0
	v_lshlrev_b32_e32 v114, 16, v188
	v_and_b32_e32 v115, 0xffff0000, v188
	v_lshlrev_b32_e32 v116, 16, v189
	v_and_b32_e32 v117, 0xffff0000, v189
	v_lshlrev_b32_e32 v118, 16, v190
	v_and_b32_e32 v119, 0xffff0000, v190
	v_lshlrev_b32_e32 v120, 16, v191
	v_and_b32_e32 v121, 0xffff0000, v191
	v_add_f32_e32 v110, v110, v114
	v_add_f32_e32 v111, v111, v115
	v_add_f32_e32 v112, v112, v116
	v_add_f32_e32 v113, v113, v117
	v_add_f32_e32 v109, v109, v121
	v_add_f32_e32 v114, v106, v118
	v_add_f32_e32 v115, v107, v119
	v_add_f32_e32 v116, v108, v120
	v_cvt_pk_bf16_f32 v106, v110, v111
	v_cvt_pk_bf16_f32 v107, v112, v113
	v_cvt_pk_bf16_f32 v108, v114, v115
	v_cvt_pk_bf16_f32 v109, v116, v109
	v_add_u32_e32 v114, s40, v151
	v_ashrrev_i32_e32 v115, 31, v114
	v_lshlrev_b64 v[114:115], 13, v[114:115]
	v_or_b32_e32 v116, v178, v154
	v_lshl_add_u64 v[114:115], v[122:123], 0, v[114:115]
	v_ashrrev_i32_e32 v117, 31, v116
	v_lshlrev_b64 v[116:117], 13, v[116:117]
	global_store_dwordx4 v[114:115], v[106:109], off
	v_lshl_add_u64 v[116:117], v[146:147], 0, v[116:117]
	s_waitcnt vmcnt(15)
	v_lshlrev_b32_e32 v106, 16, v192
	v_and_b32_e32 v107, 0xffff0000, v192
	v_lshlrev_b32_e32 v108, 16, v193
	v_and_b32_e32 v109, 0xffff0000, v193
	v_lshlrev_b32_e32 v110, 16, v194
	v_and_b32_e32 v111, 0xffff0000, v194
	v_lshlrev_b32_e32 v112, 16, v195
	v_and_b32_e32 v113, 0xffff0000, v195
	v_add_f32_e32 v102, v102, v106
	v_add_f32_e32 v103, v103, v107
	v_add_f32_e32 v104, v104, v108
	v_add_f32_e32 v105, v105, v109
	v_add_f32_e32 v101, v101, v113
	v_add_f32_e32 v106, v98, v110
	v_add_f32_e32 v107, v99, v111
	v_add_f32_e32 v108, v100, v112
	v_cvt_pk_bf16_f32 v98, v102, v103
	v_cvt_pk_bf16_f32 v99, v104, v105
	v_cvt_pk_bf16_f32 v100, v106, v107
	v_cvt_pk_bf16_f32 v101, v108, v101
	s_nop 0
	global_store_dwordx4 v[114:115], v[98:101], off offset:256
	s_waitcnt vmcnt(15)
	s_nop 0
	v_lshlrev_b32_e32 v98, 16, v196
	v_and_b32_e32 v99, 0xffff0000, v196
	v_lshlrev_b32_e32 v100, 16, v197
	v_and_b32_e32 v101, 0xffff0000, v197
	v_lshlrev_b32_e32 v102, 16, v198
	v_and_b32_e32 v103, 0xffff0000, v198
	v_lshlrev_b32_e32 v104, 16, v199
	v_and_b32_e32 v105, 0xffff0000, v199
	v_add_f32_e32 v94, v94, v98
	v_add_f32_e32 v95, v95, v99
	v_add_f32_e32 v96, v96, v100
	v_add_f32_e32 v97, v97, v101
	v_add_f32_e32 v93, v93, v105
	v_add_f32_e32 v98, v90, v102
	v_add_f32_e32 v99, v91, v103
	v_add_f32_e32 v100, v92, v104
	v_cvt_pk_bf16_f32 v90, v94, v95
	v_cvt_pk_bf16_f32 v91, v96, v97
	v_cvt_pk_bf16_f32 v92, v98, v99
	v_cvt_pk_bf16_f32 v93, v100, v93
	v_add_u32_e32 v98, s40, v153
	v_ashrrev_i32_e32 v99, 31, v98
	v_lshlrev_b64 v[98:99], 13, v[98:99]
	v_or_b32_e32 v100, v178, v156
	v_lshl_add_u64 v[98:99], v[122:123], 0, v[98:99]
	v_ashrrev_i32_e32 v101, 31, v100
	v_lshlrev_b64 v[100:101], 13, v[100:101]
	global_store_dwordx4 v[98:99], v[90:93], off
	v_lshl_add_u64 v[100:101], v[146:147], 0, v[100:101]
	s_waitcnt vmcnt(15)
	v_lshlrev_b32_e32 v90, 16, v202
	v_and_b32_e32 v91, 0xffff0000, v202
	v_lshlrev_b32_e32 v92, 16, v203
	v_and_b32_e32 v93, 0xffff0000, v203
	v_lshlrev_b32_e32 v94, 16, v204
	v_and_b32_e32 v95, 0xffff0000, v204
	v_lshlrev_b32_e32 v96, 16, v205
	v_and_b32_e32 v97, 0xffff0000, v205
	v_add_f32_e32 v86, v86, v90
	v_add_f32_e32 v87, v87, v91
	v_add_f32_e32 v88, v88, v92
	v_add_f32_e32 v89, v89, v93
	v_add_f32_e32 v85, v85, v97
	v_add_f32_e32 v90, v82, v94
	v_add_f32_e32 v91, v83, v95
	v_add_f32_e32 v92, v84, v96
	v_cvt_pk_bf16_f32 v82, v86, v87
	v_cvt_pk_bf16_f32 v83, v88, v89
	v_cvt_pk_bf16_f32 v84, v90, v91
	v_cvt_pk_bf16_f32 v85, v92, v85
	s_nop 0
	global_store_dwordx4 v[98:99], v[82:85], off offset:256
	s_waitcnt vmcnt(15)
	s_nop 0
	v_lshlrev_b32_e32 v82, 16, v206
	v_and_b32_e32 v83, 0xffff0000, v206
	v_lshlrev_b32_e32 v84, 16, v207
	v_and_b32_e32 v85, 0xffff0000, v207
	v_lshlrev_b32_e32 v86, 16, v208
	v_and_b32_e32 v87, 0xffff0000, v208
	v_lshlrev_b32_e32 v88, 16, v209
	v_and_b32_e32 v89, 0xffff0000, v209
	v_add_f32_e32 v78, v78, v82
	v_add_f32_e32 v79, v79, v83
	v_add_f32_e32 v80, v80, v84
	v_add_f32_e32 v81, v81, v85
	v_add_f32_e32 v77, v77, v89
	v_add_f32_e32 v82, v74, v86
	v_add_f32_e32 v83, v75, v87
	v_add_f32_e32 v84, v76, v88
	v_cvt_pk_bf16_f32 v74, v78, v79
	v_cvt_pk_bf16_f32 v75, v80, v81
	v_cvt_pk_bf16_f32 v76, v82, v83
	v_cvt_pk_bf16_f32 v77, v84, v77
	v_add_u32_e32 v82, s40, v155
	v_ashrrev_i32_e32 v83, 31, v82
	v_add_u32_e32 v86, s33, v169
	v_lshlrev_b64 v[82:83], 13, v[82:83]
	v_or_b32_e32 v84, v86, v158
	v_lshl_add_u64 v[82:83], v[122:123], 0, v[82:83]
	v_ashrrev_i32_e32 v85, 31, v84
	v_lshlrev_b64 v[84:85], 13, v[84:85]
	global_store_dwordx4 v[82:83], v[74:77], off
	v_lshl_add_u64 v[84:85], v[146:147], 0, v[84:85]
	s_waitcnt vmcnt(15)
	v_lshlrev_b32_e32 v74, 16, v210
	v_and_b32_e32 v75, 0xffff0000, v210
	v_lshlrev_b32_e32 v76, 16, v211
	v_and_b32_e32 v77, 0xffff0000, v211
	v_lshlrev_b32_e32 v78, 16, v212
	v_and_b32_e32 v79, 0xffff0000, v212
	v_lshlrev_b32_e32 v80, 16, v213
	v_and_b32_e32 v81, 0xffff0000, v213
	v_add_f32_e32 v70, v70, v74
	v_add_f32_e32 v71, v71, v75
	v_add_f32_e32 v72, v72, v76
	v_add_f32_e32 v73, v73, v77
	v_add_f32_e32 v69, v69, v81
	v_add_f32_e32 v74, v66, v78
	v_add_f32_e32 v75, v67, v79
	v_add_f32_e32 v76, v68, v80
	v_cvt_pk_bf16_f32 v66, v70, v71
	v_cvt_pk_bf16_f32 v67, v72, v73
	v_cvt_pk_bf16_f32 v68, v74, v75
	v_cvt_pk_bf16_f32 v69, v76, v69
	s_nop 0
	global_store_dwordx4 v[82:83], v[66:69], off offset:256
	s_waitcnt vmcnt(15)
; __device__ __forceinline__ float bf_lo(unsigned w) { return __uint_as_float(w << 16); }
; __device__ __forceinline__ float bf_hi(unsigned w) { return __uint_as_float(w & 0xffff0000u); }
; __device__ __forceinline__ v4u pack8(f32x4 a, f32x4 b) { v4u w; w.x = cvt_pk_bf16(a[0], a[1]); w.y = cvt_pk_bf16(a[2], a[3]); w.z = cvt_pk_bf16(b[0], b[1]); w.w = cvt_pk_bf16(b[2], b[3]); return w; }
;     __device__ __forceinline__ void operator()(const f32x4 (&acc)[2][2][4][2], const Unit& u, int wr, int wc, int fr, int fq) const {
;         const bf16* const X1B = (const bf16*)(ws + WS_X1B); bf16* const X2B = (bf16*)(ws + WS_X2B);
;         const int col0 = u.pn * 256 + wc * 32 + 8 * fq;
; #pragma unroll
;         for (int ai = 0; ai < 2; ++ai)
; #pragma unroll
;             for (int m = 0; m < 4; ++m) { const int p = ai * 128 + wr * 64 + m * 16 + fr;
;                 const bf16* sr = X1B + (size_t)(u.pm * 256 + perm_row(p)) * DM + col0; bf16* dr = X2B + (size_t)(u.pm * 256 + p) * DM + col0;
; #pragma unroll
;                 for (int bj = 0; bj < 2; ++bj) { const v4u x = *(const v4u*)(sr + bj * 128); const f32x4 a0 = acc[ai][bj][m][0], a1 = acc[ai][bj][m][1];
;                     const f32x4 v0 = {bf_lo(x.x) + a0[0], bf_hi(x.x) + a0[1], bf_lo(x.y) + a0[2], bf_hi(x.y) + a0[3]};
;                     const f32x4 v1 = {bf_lo(x.z) + a1[0], bf_hi(x.z) + a1[1], bf_lo(x.w) + a1[2], bf_hi(x.w) + a1[3]};
;                     *(v4u*)(dr + bj * 128) = pack8(v0, v1); } }
;     }
	s_nop 0
	v_lshlrev_b32_e32 v66, 16, v214
	v_and_b32_e32 v67, 0xffff0000, v214
	v_lshlrev_b32_e32 v68, 16, v215
	v_and_b32_e32 v69, 0xffff0000, v215
	v_lshlrev_b32_e32 v70, 16, v216
	v_and_b32_e32 v71, 0xffff0000, v216
	v_lshlrev_b32_e32 v72, 16, v217
	v_and_b32_e32 v73, 0xffff0000, v217
	v_add_f32_e32 v62, v62, v66
	v_add_f32_e32 v63, v63, v67
	v_add_f32_e32 v64, v64, v68
	v_add_f32_e32 v65, v65, v69
	v_add_f32_e32 v61, v61, v73
	v_add_f32_e32 v66, v58, v70
	v_add_f32_e32 v67, v59, v71
	v_add_f32_e32 v68, v60, v72
	v_cvt_pk_bf16_f32 v58, v62, v63
	v_cvt_pk_bf16_f32 v59, v64, v65
	v_cvt_pk_bf16_f32 v60, v66, v67
	v_cvt_pk_bf16_f32 v61, v68, v61
	v_add_u32_e32 v66, s40, v157
	v_ashrrev_i32_e32 v67, 31, v66
	v_lshlrev_b64 v[66:67], 13, v[66:67]
	v_or_b32_e32 v68, v86, v160
	v_lshl_add_u64 v[66:67], v[122:123], 0, v[66:67]
	v_ashrrev_i32_e32 v69, 31, v68
	v_lshlrev_b64 v[68:69], 13, v[68:69]
	global_store_dwordx4 v[66:67], v[58:61], off
	v_lshl_add_u64 v[68:69], v[146:147], 0, v[68:69]
	s_waitcnt vmcnt(15)
	v_lshlrev_b32_e32 v58, 16, v218
	v_and_b32_e32 v59, 0xffff0000, v218
	v_lshlrev_b32_e32 v60, 16, v219
	v_and_b32_e32 v61, 0xffff0000, v219
	v_lshlrev_b32_e32 v62, 16, v220
	v_and_b32_e32 v63, 0xffff0000, v220
	v_lshlrev_b32_e32 v64, 16, v221
	v_and_b32_e32 v65, 0xffff0000, v221
	v_add_f32_e32 v54, v54, v58
	v_add_f32_e32 v55, v55, v59
	v_add_f32_e32 v56, v56, v60
	v_add_f32_e32 v57, v57, v61
	v_add_f32_e32 v53, v53, v65
	v_add_f32_e32 v58, v50, v62
	v_add_f32_e32 v59, v51, v63
	v_add_f32_e32 v60, v52, v64
	v_cvt_pk_bf16_f32 v50, v54, v55
	v_cvt_pk_bf16_f32 v51, v56, v57
	v_cvt_pk_bf16_f32 v52, v58, v59
	v_cvt_pk_bf16_f32 v53, v60, v53
	s_nop 0
	global_store_dwordx4 v[66:67], v[50:53], off offset:256
	s_waitcnt vmcnt(15)
	s_nop 0
	v_lshlrev_b32_e32 v50, 16, v222
	v_and_b32_e32 v51, 0xffff0000, v222
	v_lshlrev_b32_e32 v52, 16, v223
	v_and_b32_e32 v53, 0xffff0000, v223
	v_lshlrev_b32_e32 v54, 16, v224
	v_and_b32_e32 v55, 0xffff0000, v224
	v_lshlrev_b32_e32 v56, 16, v225
	v_and_b32_e32 v57, 0xffff0000, v225
	v_add_f32_e32 v46, v46, v50
	v_add_f32_e32 v47, v47, v51
	v_add_f32_e32 v48, v48, v52
	v_add_f32_e32 v49, v49, v53
	v_add_f32_e32 v45, v45, v57
	v_add_f32_e32 v50, v42, v54
	v_add_f32_e32 v51, v43, v55
	v_add_f32_e32 v52, v44, v56
	v_cvt_pk_bf16_f32 v42, v46, v47
	v_cvt_pk_bf16_f32 v43, v48, v49
	v_cvt_pk_bf16_f32 v44, v50, v51
	v_cvt_pk_bf16_f32 v45, v52, v45
	v_add_u32_e32 v50, s40, v159
	v_ashrrev_i32_e32 v51, 31, v50
	v_lshlrev_b64 v[50:51], 13, v[50:51]
	v_or_b32_e32 v52, v86, v162
	v_lshl_add_u64 v[50:51], v[122:123], 0, v[50:51]
	v_ashrrev_i32_e32 v53, 31, v52
	v_lshlrev_b64 v[52:53], 13, v[52:53]
	global_store_dwordx4 v[50:51], v[42:45], off
	v_lshl_add_u64 v[52:53], v[146:147], 0, v[52:53]
	s_waitcnt vmcnt(15)
	v_lshlrev_b32_e32 v42, 16, v226
	v_and_b32_e32 v43, 0xffff0000, v226
	v_lshlrev_b32_e32 v44, 16, v227
	v_and_b32_e32 v45, 0xffff0000, v227
	v_lshlrev_b32_e32 v46, 16, v228
	v_and_b32_e32 v47, 0xffff0000, v228
	v_lshlrev_b32_e32 v48, 16, v229
	v_and_b32_e32 v49, 0xffff0000, v229
	v_add_f32_e32 v38, v38, v42
	v_add_f32_e32 v39, v39, v43
	v_add_f32_e32 v40, v40, v44
	v_add_f32_e32 v41, v41, v45
	v_add_f32_e32 v37, v37, v49
	v_add_f32_e32 v42, v34, v46
	v_add_f32_e32 v43, v35, v47
	v_add_f32_e32 v44, v36, v48
	v_cvt_pk_bf16_f32 v34, v38, v39
	v_cvt_pk_bf16_f32 v35, v40, v41
	v_cvt_pk_bf16_f32 v36, v42, v43
	v_cvt_pk_bf16_f32 v37, v44, v37
	s_nop 0
	global_store_dwordx4 v[50:51], v[34:37], off offset:256
	s_waitcnt vmcnt(15)
	s_nop 0
	v_lshlrev_b32_e32 v34, 16, v230
	v_and_b32_e32 v35, 0xffff0000, v230
	v_lshlrev_b32_e32 v36, 16, v231
	v_and_b32_e32 v37, 0xffff0000, v231
	v_lshlrev_b32_e32 v38, 16, v232
	v_and_b32_e32 v39, 0xffff0000, v232
	v_lshlrev_b32_e32 v40, 16, v233
	v_and_b32_e32 v41, 0xffff0000, v233
	v_add_f32_e32 v30, v30, v34
	v_add_f32_e32 v31, v31, v35
	v_add_f32_e32 v32, v32, v36
	v_add_f32_e32 v33, v33, v37
	v_add_f32_e32 v29, v29, v41
	v_add_f32_e32 v34, v26, v38
	v_add_f32_e32 v35, v27, v39
	v_add_f32_e32 v36, v28, v40
	v_cvt_pk_bf16_f32 v26, v30, v31
	v_cvt_pk_bf16_f32 v27, v32, v33
	v_cvt_pk_bf16_f32 v28, v34, v35
	v_cvt_pk_bf16_f32 v29, v36, v29
	v_add_u32_e32 v34, s40, v161
	v_ashrrev_i32_e32 v35, 31, v34
	v_lshlrev_b64 v[34:35], 13, v[34:35]
	v_or_b32_e32 v36, v86, v164
	v_lshl_add_u64 v[34:35], v[122:123], 0, v[34:35]
	v_ashrrev_i32_e32 v37, 31, v36
	v_lshlrev_b64 v[36:37], 13, v[36:37]
	global_store_dwordx4 v[34:35], v[26:29], off
	v_lshl_add_u64 v[36:37], v[146:147], 0, v[36:37]
	s_waitcnt vmcnt(15)
	v_lshlrev_b32_e32 v26, 16, v234
	v_and_b32_e32 v27, 0xffff0000, v234
	v_lshlrev_b32_e32 v28, 16, v235
	v_and_b32_e32 v29, 0xffff0000, v235
	v_lshlrev_b32_e32 v30, 16, v236
	v_and_b32_e32 v31, 0xffff0000, v236
	v_lshlrev_b32_e32 v32, 16, v237
	v_and_b32_e32 v33, 0xffff0000, v237
	v_add_f32_e32 v22, v22, v26
	v_add_f32_e32 v23, v23, v27
	v_add_f32_e32 v24, v24, v28
	v_add_f32_e32 v25, v25, v29
	v_add_f32_e32 v21, v21, v33
	v_add_f32_e32 v26, v18, v30
	v_add_f32_e32 v27, v19, v31
	v_add_f32_e32 v28, v20, v32
	v_cvt_pk_bf16_f32 v18, v22, v23
	v_cvt_pk_bf16_f32 v19, v24, v25
	v_cvt_pk_bf16_f32 v20, v26, v27
	v_cvt_pk_bf16_f32 v21, v28, v21
	s_nop 0
	global_store_dwordx4 v[34:35], v[18:21], off offset:256
	s_waitcnt vmcnt(15)
	s_nop 0
	v_lshlrev_b32_e32 v18, 16, v238
	v_and_b32_e32 v19, 0xffff0000, v238
	v_lshlrev_b32_e32 v20, 16, v239
	v_and_b32_e32 v21, 0xffff0000, v239
	v_lshlrev_b32_e32 v22, 16, v240
	v_and_b32_e32 v23, 0xffff0000, v240
	v_lshlrev_b32_e32 v24, 16, v241
	v_and_b32_e32 v25, 0xffff0000, v241
	v_add_f32_e32 v14, v14, v18
	v_add_f32_e32 v15, v15, v19
	v_add_f32_e32 v16, v16, v20
	v_add_f32_e32 v17, v17, v21
	v_add_f32_e32 v13, v13, v25
	v_add_f32_e32 v18, v10, v22
	v_add_f32_e32 v19, v11, v23
	v_add_f32_e32 v20, v12, v24
	v_cvt_pk_bf16_f32 v10, v14, v15
	v_cvt_pk_bf16_f32 v11, v16, v17
	v_cvt_pk_bf16_f32 v12, v18, v19
	v_cvt_pk_bf16_f32 v13, v20, v13
	v_add_u32_e32 v18, s40, v163
	v_ashrrev_i32_e32 v19, 31, v18
	v_lshlrev_b64 v[18:19], 13, v[18:19]
	v_lshl_add_u64 v[18:19], v[122:123], 0, v[18:19]
	global_store_dwordx4 v[18:19], v[10:13], off
	s_waitcnt vmcnt(15)
	s_nop 0
	v_lshlrev_b32_e32 v10, 16, v242
	v_and_b32_e32 v11, 0xffff0000, v242
	v_lshlrev_b32_e32 v12, 16, v243
	v_and_b32_e32 v13, 0xffff0000, v243
	v_lshlrev_b32_e32 v14, 16, v244
	v_and_b32_e32 v15, 0xffff0000, v244
	v_lshlrev_b32_e32 v16, 16, v245
	v_and_b32_e32 v17, 0xffff0000, v245
	v_add_f32_e32 v5, v5, v17
	v_add_f32_e32 v6, v6, v10
	v_add_f32_e32 v7, v7, v11
	v_add_f32_e32 v8, v8, v12
	v_add_f32_e32 v9, v9, v13
	v_add_f32_e32 v10, v2, v14
	v_add_f32_e32 v11, v3, v15
	v_add_f32_e32 v12, v4, v16
	v_cvt_pk_bf16_f32 v2, v6, v7
	v_cvt_pk_bf16_f32 v3, v8, v9
	v_cvt_pk_bf16_f32 v4, v10, v11
	v_cvt_pk_bf16_f32 v5, v12, v5
	global_store_dwordx4 v[18:19], v[2:5], off offset:256
	s_cbranch_vccnz .LBB0_1719
	s_andn2_b64 vcc, exec, s[8:9]
	s_cbranch_vccnz .LBB0_1718
	s_barrier
	s_branch .LBB0_1718
